# A/B: v3 with every s_setprio deleted from the eight K-loops
# speedup vs baseline: 1.0012x; 1.0012x over previous
.LBB0_121:
	ds_read_b128 v[164:167], v131
	ds_read_b128 v[168:171], v131 offset:1024
	ds_read_b128 v[172:175], v131 offset:2048
	ds_read_b128 v[176:179], v131 offset:3072
	ds_read_b128 v[180:183], v160
	ds_read_b128 v[184:187], v160 offset:1024
	ds_read_b128 v[188:191], v160 offset:2048
	ds_read_b128 v[192:195], v160 offset:3072
	s_add_i32 s55, s52, 0xfffc0080
	s_cmp_eq_u32 s54, 12
	s_cselect_b32 s57, s16, s55
	s_cselect_b32 s56, s17, s53
	s_or_b32 s55, s57, 0x80
	ds_read_b128 v[196:199], v161
	ds_read_b128 v[200:203], v161 offset:1024
	ds_read_b128 v[204:207], v161 offset:2048
	ds_read_b128 v[208:211], v161 offset:3072
	ds_read_b128 v[212:215], v161 offset:4096
	ds_read_b128 v[216:219], v161 offset:5120
	ds_read_b128 v[220:223], v161 offset:6144
	ds_read_b128 v[224:227], v161 offset:7168
	s_mov_b32 m0, s40
	s_nop 0
	buffer_load_dwordx4 v156, s[12:15], s52 offen lds
	s_nop 0
	s_mov_b32 m0, s41
	s_nop 0
	buffer_load_dwordx4 v157, s[12:15], s52 offen lds
	s_waitcnt vmcnt(8)
	s_waitcnt lgkmcnt(0)
	s_barrier
	s_waitcnt lgkmcnt(7)
	v_mfma_f32_16x16x32_bf16 v[126:129], v[164:167], v[196:199], v[126:129]
	v_mfma_f32_16x16x32_bf16 v[122:125], v[172:175], v[196:199], v[122:125]
	s_waitcnt lgkmcnt(5)
	v_mfma_f32_16x16x32_bf16 v[118:121], v[164:167], v[204:207], v[118:121]
	v_mfma_f32_16x16x32_bf16 v[110:113], v[172:175], v[204:207], v[110:113]
	s_waitcnt lgkmcnt(3)
	v_mfma_f32_16x16x32_bf16 v[102:105], v[164:167], v[212:215], v[102:105]
	v_mfma_f32_16x16x32_bf16 v[94:97], v[172:175], v[212:215], v[94:97]
	s_waitcnt lgkmcnt(1)
	v_mfma_f32_16x16x32_bf16 v[86:89], v[164:167], v[220:223], v[86:89]
	v_mfma_f32_16x16x32_bf16 v[78:81], v[172:175], v[220:223], v[78:81]
	v_mfma_f32_16x16x32_bf16 v[126:129], v[168:171], v[200:203], v[126:129]
	v_mfma_f32_16x16x32_bf16 v[122:125], v[176:179], v[200:203], v[122:125]
	v_mfma_f32_16x16x32_bf16 v[118:121], v[168:171], v[208:211], v[118:121]
	v_mfma_f32_16x16x32_bf16 v[110:113], v[176:179], v[208:211], v[110:113]
	v_mfma_f32_16x16x32_bf16 v[102:105], v[168:171], v[216:219], v[102:105]
	v_mfma_f32_16x16x32_bf16 v[94:97], v[176:179], v[216:219], v[94:97]
	s_waitcnt lgkmcnt(0)
	v_mfma_f32_16x16x32_bf16 v[86:89], v[168:171], v[224:227], v[86:89]
	v_mfma_f32_16x16x32_bf16 v[78:81], v[176:179], v[224:227], v[78:81]
	v_mfma_f32_16x16x32_bf16 v[114:117], v[180:183], v[196:199], v[114:117]
	v_mfma_f32_16x16x32_bf16 v[106:109], v[188:191], v[196:199], v[106:109]
	v_mfma_f32_16x16x32_bf16 v[98:101], v[180:183], v[204:207], v[98:101]
	v_mfma_f32_16x16x32_bf16 v[90:93], v[188:191], v[204:207], v[90:93]
	v_mfma_f32_16x16x32_bf16 v[82:85], v[180:183], v[212:215], v[82:85]
	v_mfma_f32_16x16x32_bf16 v[74:77], v[188:191], v[212:215], v[74:77]
	v_mfma_f32_16x16x32_bf16 v[70:73], v[180:183], v[220:223], v[70:73]
	v_mfma_f32_16x16x32_bf16 v[66:69], v[188:191], v[220:223], v[66:69]
	v_mfma_f32_16x16x32_bf16 v[114:117], v[184:187], v[200:203], v[114:117]
	v_mfma_f32_16x16x32_bf16 v[106:109], v[192:195], v[200:203], v[106:109]
	v_mfma_f32_16x16x32_bf16 v[98:101], v[184:187], v[208:211], v[98:101]
	v_mfma_f32_16x16x32_bf16 v[90:93], v[192:195], v[208:211], v[90:93]
	v_mfma_f32_16x16x32_bf16 v[82:85], v[184:187], v[216:219], v[82:85]
	v_mfma_f32_16x16x32_bf16 v[74:77], v[192:195], v[216:219], v[74:77]
	v_mfma_f32_16x16x32_bf16 v[70:73], v[184:187], v[224:227], v[70:73]
	v_mfma_f32_16x16x32_bf16 v[66:69], v[192:195], v[224:227], v[66:69]
	s_barrier
	ds_read_b128 v[196:199], v161 offset:16384
	ds_read_b128 v[200:203], v161 offset:17408
	ds_read_b128 v[204:207], v161 offset:18432
	ds_read_b128 v[208:211], v161 offset:19456
	ds_read_b128 v[212:215], v161 offset:20480
	ds_read_b128 v[216:219], v161 offset:21504
	ds_read_b128 v[220:223], v161 offset:22528
	ds_read_b128 v[224:227], v161 offset:23552
	s_mov_b32 m0, s22
	s_nop 0
	buffer_load_dwordx4 v154, s[8:11], s56 offen lds
	s_add_i32 s58, s56, 0x40000
	s_mov_b32 m0, s23
	s_nop 0
	buffer_load_dwordx4 v155, s[8:11], s56 offen lds
	s_nop 0
	s_mov_b32 m0, s24
	s_nop 0
	buffer_load_dwordx4 v154, s[8:11], s58 offen lds
	s_nop 0
	s_mov_b32 m0, s25
	s_nop 0
	buffer_load_dwordx4 v155, s[8:11], s58 offen lds
	s_nop 0
	s_mov_b32 m0, s21
	s_nop 0
	buffer_load_dwordx4 v156, s[12:15], s57 offen lds
	s_nop 0
	s_mov_b32 m0, s27
	s_nop 0
	buffer_load_dwordx4 v157, s[12:15], s57 offen lds
	s_waitcnt vmcnt(8)
	s_waitcnt lgkmcnt(0)
	s_barrier
	s_waitcnt lgkmcnt(7)
	v_mfma_f32_16x16x32_bf16 v[62:65], v[164:167], v[196:199], v[62:65]
	v_mfma_f32_16x16x32_bf16 v[58:61], v[172:175], v[196:199], v[58:61]
	s_waitcnt lgkmcnt(5)
	v_mfma_f32_16x16x32_bf16 v[54:57], v[164:167], v[204:207], v[54:57]
	v_mfma_f32_16x16x32_bf16 v[46:49], v[172:175], v[204:207], v[46:49]
	s_waitcnt lgkmcnt(3)
	v_mfma_f32_16x16x32_bf16 v[38:41], v[164:167], v[212:215], v[38:41]
	v_mfma_f32_16x16x32_bf16 v[30:33], v[172:175], v[212:215], v[30:33]
	s_waitcnt lgkmcnt(1)
	v_mfma_f32_16x16x32_bf16 v[22:25], v[164:167], v[220:223], v[22:25]
	v_mfma_f32_16x16x32_bf16 v[14:17], v[172:175], v[220:223], v[14:17]
	v_mfma_f32_16x16x32_bf16 v[62:65], v[168:171], v[200:203], v[62:65]
	v_mfma_f32_16x16x32_bf16 v[58:61], v[176:179], v[200:203], v[58:61]
	v_mfma_f32_16x16x32_bf16 v[54:57], v[168:171], v[208:211], v[54:57]
	v_mfma_f32_16x16x32_bf16 v[46:49], v[176:179], v[208:211], v[46:49]
	v_mfma_f32_16x16x32_bf16 v[38:41], v[168:171], v[216:219], v[38:41]
	v_mfma_f32_16x16x32_bf16 v[30:33], v[176:179], v[216:219], v[30:33]
	s_waitcnt lgkmcnt(0)
	v_mfma_f32_16x16x32_bf16 v[22:25], v[168:171], v[224:227], v[22:25]
	v_mfma_f32_16x16x32_bf16 v[14:17], v[176:179], v[224:227], v[14:17]
	v_mfma_f32_16x16x32_bf16 v[50:53], v[180:183], v[196:199], v[50:53]
	v_mfma_f32_16x16x32_bf16 v[42:45], v[188:191], v[196:199], v[42:45]
	v_mfma_f32_16x16x32_bf16 v[34:37], v[180:183], v[204:207], v[34:37]
	v_mfma_f32_16x16x32_bf16 v[26:29], v[188:191], v[204:207], v[26:29]
	v_mfma_f32_16x16x32_bf16 v[18:21], v[180:183], v[212:215], v[18:21]
	v_mfma_f32_16x16x32_bf16 v[10:13], v[188:191], v[212:215], v[10:13]
	v_mfma_f32_16x16x32_bf16 v[6:9], v[180:183], v[220:223], v[6:9]
	v_mfma_f32_16x16x32_bf16 v[2:5], v[188:191], v[220:223], v[2:5]
	v_mfma_f32_16x16x32_bf16 v[50:53], v[184:187], v[200:203], v[50:53]
	v_mfma_f32_16x16x32_bf16 v[42:45], v[192:195], v[200:203], v[42:45]
	v_mfma_f32_16x16x32_bf16 v[34:37], v[184:187], v[208:211], v[34:37]
	v_mfma_f32_16x16x32_bf16 v[26:29], v[192:195], v[208:211], v[26:29]
	v_mfma_f32_16x16x32_bf16 v[18:21], v[184:187], v[216:219], v[18:21]
	v_mfma_f32_16x16x32_bf16 v[10:13], v[192:195], v[216:219], v[10:13]
	v_mfma_f32_16x16x32_bf16 v[6:9], v[184:187], v[224:227], v[6:9]
	v_mfma_f32_16x16x32_bf16 v[2:5], v[192:195], v[224:227], v[2:5]
	s_barrier
	ds_read_b128 v[164:167], v162
	ds_read_b128 v[168:171], v162 offset:1024
	ds_read_b128 v[172:175], v162 offset:2048
	ds_read_b128 v[176:179], v162 offset:3072
	ds_read_b128 v[180:183], v163
	ds_read_b128 v[184:187], v163 offset:1024
	ds_read_b128 v[188:191], v163 offset:2048
	ds_read_b128 v[192:195], v163 offset:3072
	ds_read_b128 v[196:199], v161 offset:32768
	ds_read_b128 v[200:203], v161 offset:33792
	ds_read_b128 v[204:207], v161 offset:34816
	ds_read_b128 v[208:211], v161 offset:35840
	ds_read_b128 v[212:215], v161 offset:36864
	ds_read_b128 v[216:219], v161 offset:37888
	ds_read_b128 v[220:223], v161 offset:38912
	ds_read_b128 v[224:227], v161 offset:39936
	s_add_i32 s57, s57, 0x40000
	s_mov_b32 m0, s28
	s_nop 0
	buffer_load_dwordx4 v156, s[12:15], s57 offen lds
	s_nop 0
	s_mov_b32 m0, s30
	s_nop 0
	buffer_load_dwordx4 v157, s[12:15], s57 offen lds
	s_waitcnt vmcnt(8)
	s_waitcnt lgkmcnt(0)
	s_barrier
	s_waitcnt lgkmcnt(7)
	v_mfma_f32_16x16x32_bf16 v[126:129], v[164:167], v[196:199], v[126:129]
	v_mfma_f32_16x16x32_bf16 v[122:125], v[172:175], v[196:199], v[122:125]
	s_waitcnt lgkmcnt(5)
	v_mfma_f32_16x16x32_bf16 v[118:121], v[164:167], v[204:207], v[118:121]
	v_mfma_f32_16x16x32_bf16 v[110:113], v[172:175], v[204:207], v[110:113]
	s_waitcnt lgkmcnt(3)
	v_mfma_f32_16x16x32_bf16 v[102:105], v[164:167], v[212:215], v[102:105]
	v_mfma_f32_16x16x32_bf16 v[94:97], v[172:175], v[212:215], v[94:97]
	s_waitcnt lgkmcnt(1)
	v_mfma_f32_16x16x32_bf16 v[86:89], v[164:167], v[220:223], v[86:89]
	v_mfma_f32_16x16x32_bf16 v[78:81], v[172:175], v[220:223], v[78:81]
	v_mfma_f32_16x16x32_bf16 v[126:129], v[168:171], v[200:203], v[126:129]
	v_mfma_f32_16x16x32_bf16 v[122:125], v[176:179], v[200:203], v[122:125]
	v_mfma_f32_16x16x32_bf16 v[118:121], v[168:171], v[208:211], v[118:121]
	v_mfma_f32_16x16x32_bf16 v[110:113], v[176:179], v[208:211], v[110:113]
	v_mfma_f32_16x16x32_bf16 v[102:105], v[168:171], v[216:219], v[102:105]
	v_mfma_f32_16x16x32_bf16 v[94:97], v[176:179], v[216:219], v[94:97]
	s_waitcnt lgkmcnt(0)
	v_mfma_f32_16x16x32_bf16 v[86:89], v[168:171], v[224:227], v[86:89]
	v_mfma_f32_16x16x32_bf16 v[78:81], v[176:179], v[224:227], v[78:81]
	v_mfma_f32_16x16x32_bf16 v[114:117], v[180:183], v[196:199], v[114:117]
	v_mfma_f32_16x16x32_bf16 v[106:109], v[188:191], v[196:199], v[106:109]
	v_mfma_f32_16x16x32_bf16 v[98:101], v[180:183], v[204:207], v[98:101]
	v_mfma_f32_16x16x32_bf16 v[90:93], v[188:191], v[204:207], v[90:93]
	v_mfma_f32_16x16x32_bf16 v[82:85], v[180:183], v[212:215], v[82:85]
	v_mfma_f32_16x16x32_bf16 v[74:77], v[188:191], v[212:215], v[74:77]
	v_mfma_f32_16x16x32_bf16 v[70:73], v[180:183], v[220:223], v[70:73]
	v_mfma_f32_16x16x32_bf16 v[66:69], v[188:191], v[220:223], v[66:69]
	v_mfma_f32_16x16x32_bf16 v[114:117], v[184:187], v[200:203], v[114:117]
	v_mfma_f32_16x16x32_bf16 v[106:109], v[192:195], v[200:203], v[106:109]
	v_mfma_f32_16x16x32_bf16 v[98:101], v[184:187], v[208:211], v[98:101]
	v_mfma_f32_16x16x32_bf16 v[90:93], v[192:195], v[208:211], v[90:93]
	v_mfma_f32_16x16x32_bf16 v[82:85], v[184:187], v[216:219], v[82:85]
	v_mfma_f32_16x16x32_bf16 v[74:77], v[192:195], v[216:219], v[74:77]
	v_mfma_f32_16x16x32_bf16 v[70:73], v[184:187], v[224:227], v[70:73]
	v_mfma_f32_16x16x32_bf16 v[66:69], v[192:195], v[224:227], v[66:69]
	s_barrier
	ds_read_b128 v[196:199], v161 offset:49152
	ds_read_b128 v[200:203], v161 offset:50176
	ds_read_b128 v[204:207], v161 offset:51200
	ds_read_b128 v[208:211], v161 offset:52224
	ds_read_b128 v[212:215], v161 offset:53248
	ds_read_b128 v[216:219], v161 offset:54272
	ds_read_b128 v[220:223], v161 offset:55296
	ds_read_b128 v[224:227], v161 offset:56320
	s_or_b32 s57, s56, 0x80
	s_mov_b32 m0, s34
	s_nop 0
	buffer_load_dwordx4 v154, s[8:11], s57 offen lds
	s_add_i32 s56, s56, 0x40080
	s_mov_b32 m0, s35
	s_nop 0
	buffer_load_dwordx4 v155, s[8:11], s57 offen lds
	s_nop 0
	s_mov_b32 m0, s38
	s_nop 0
	buffer_load_dwordx4 v154, s[8:11], s56 offen lds
	s_nop 0
	s_mov_b32 m0, s39
	s_nop 0
	buffer_load_dwordx4 v155, s[8:11], s56 offen lds
	s_nop 0
	s_mov_b32 m0, s36
	s_nop 0
	buffer_load_dwordx4 v156, s[12:15], s55 offen lds
	s_nop 0
	s_mov_b32 m0, s37
	s_nop 0
	buffer_load_dwordx4 v157, s[12:15], s55 offen lds
	s_waitcnt vmcnt(8)
	s_waitcnt lgkmcnt(0)
	s_barrier
	s_waitcnt lgkmcnt(7)
	v_mfma_f32_16x16x32_bf16 v[62:65], v[164:167], v[196:199], v[62:65]
	v_mfma_f32_16x16x32_bf16 v[58:61], v[172:175], v[196:199], v[58:61]
	s_waitcnt lgkmcnt(5)
	v_mfma_f32_16x16x32_bf16 v[54:57], v[164:167], v[204:207], v[54:57]
	v_mfma_f32_16x16x32_bf16 v[46:49], v[172:175], v[204:207], v[46:49]
	s_waitcnt lgkmcnt(3)
	v_mfma_f32_16x16x32_bf16 v[38:41], v[164:167], v[212:215], v[38:41]
	v_mfma_f32_16x16x32_bf16 v[30:33], v[172:175], v[212:215], v[30:33]
	s_waitcnt lgkmcnt(1)
	v_mfma_f32_16x16x32_bf16 v[22:25], v[164:167], v[220:223], v[22:25]
	v_mfma_f32_16x16x32_bf16 v[14:17], v[172:175], v[220:223], v[14:17]
	v_mfma_f32_16x16x32_bf16 v[62:65], v[168:171], v[200:203], v[62:65]
	v_mfma_f32_16x16x32_bf16 v[58:61], v[176:179], v[200:203], v[58:61]
	v_mfma_f32_16x16x32_bf16 v[54:57], v[168:171], v[208:211], v[54:57]
	v_mfma_f32_16x16x32_bf16 v[46:49], v[176:179], v[208:211], v[46:49]
	v_mfma_f32_16x16x32_bf16 v[38:41], v[168:171], v[216:219], v[38:41]
	v_mfma_f32_16x16x32_bf16 v[30:33], v[176:179], v[216:219], v[30:33]
	s_waitcnt lgkmcnt(0)
	v_mfma_f32_16x16x32_bf16 v[22:25], v[168:171], v[224:227], v[22:25]
	v_mfma_f32_16x16x32_bf16 v[14:17], v[176:179], v[224:227], v[14:17]
	v_mfma_f32_16x16x32_bf16 v[50:53], v[180:183], v[196:199], v[50:53]
	v_mfma_f32_16x16x32_bf16 v[42:45], v[188:191], v[196:199], v[42:45]
	v_mfma_f32_16x16x32_bf16 v[34:37], v[180:183], v[204:207], v[34:37]
	v_mfma_f32_16x16x32_bf16 v[26:29], v[188:191], v[204:207], v[26:29]
	v_mfma_f32_16x16x32_bf16 v[18:21], v[180:183], v[212:215], v[18:21]
	v_mfma_f32_16x16x32_bf16 v[10:13], v[188:191], v[212:215], v[10:13]
	v_mfma_f32_16x16x32_bf16 v[6:9], v[180:183], v[220:223], v[6:9]
	v_mfma_f32_16x16x32_bf16 v[2:5], v[188:191], v[220:223], v[2:5]
	v_mfma_f32_16x16x32_bf16 v[50:53], v[184:187], v[200:203], v[50:53]
	v_mfma_f32_16x16x32_bf16 v[42:45], v[192:195], v[200:203], v[42:45]
	v_mfma_f32_16x16x32_bf16 v[34:37], v[184:187], v[208:211], v[34:37]
	v_mfma_f32_16x16x32_bf16 v[26:29], v[192:195], v[208:211], v[26:29]
	v_mfma_f32_16x16x32_bf16 v[18:21], v[184:187], v[216:219], v[18:21]
	v_mfma_f32_16x16x32_bf16 v[10:13], v[192:195], v[216:219], v[10:13]
	v_mfma_f32_16x16x32_bf16 v[6:9], v[184:187], v[224:227], v[6:9]
	v_mfma_f32_16x16x32_bf16 v[2:5], v[192:195], v[224:227], v[2:5]
	s_barrier
	s_add_i32 s54, s54, 2
	s_addk_i32 s52, 0x100
	s_addk_i32 s53, 0x100
	s_cmp_gt_u32 s54, 13
	s_cbranch_scc0 .LBB0_121
	s_and_b64 vcc, exec, s[6:7]
	s_cbranch_vccz .LBB0_126
	s_barrier
	s_cmp_gt_i32 s46, 3
	s_mov_b64 s[16:17], -1
	s_cbranch_scc1 .LBB0_127

.LBB0_223:
	v_add_u32_e32 v150, 0x10000, v132
	v_add_u32_e32 v166, 0x14000, v132
	ds_read_b128 v[134:137], v150
	ds_read_b128 v[142:145], v150 offset:1024
	ds_read_b128 v[146:149], v150 offset:2048
	ds_read_b128 v[150:153], v150 offset:3072
	ds_read_b128 v[154:157], v166
	ds_read_b128 v[158:161], v166 offset:1024
	ds_read_b128 v[162:165], v166 offset:2048
	ds_read_b128 v[166:169], v166 offset:3072
	s_add_i32 s63, s39, s60
	s_add_i32 s62, s34, s60
	s_add_i32 s61, s63, 0x800
	s_addk_i32 s62, 0x800
	s_cmp_eq_u32 s60, 0
	s_cselect_b32 s64, s55, s61
	s_cselect_b32 s62, s58, s62
	s_or_b32 s61, s64, 0x80
	ds_read_b128 v[170:173], v133
	ds_read_b128 v[174:177], v133 offset:1024
	ds_read_b128 v[178:181], v133 offset:2048
	ds_read_b128 v[182:185], v133 offset:3072
	ds_read_b128 v[186:189], v133 offset:4096
	ds_read_b128 v[190:193], v133 offset:5120
	ds_read_b128 v[194:197], v133 offset:6144
	ds_read_b128 v[198:201], v133 offset:7168
	s_add_i32 s63, s63, 0x40780
	s_mov_b32 m0, s49
	s_nop 0
	buffer_load_dwordx4 v130, s[12:15], s63 offen lds
	s_nop 0
	s_mov_b32 m0, s50
	s_nop 0
	buffer_load_dwordx4 v131, s[12:15], s63 offen lds
	s_waitcnt vmcnt(8)
	s_waitcnt lgkmcnt(0)
	s_barrier
	s_waitcnt lgkmcnt(7)
	v_mfma_f32_16x16x32_bf16 v[138:141], v[134:137], v[170:173], v[138:141]
	v_mfma_f32_16x16x32_bf16 v[126:129], v[146:149], v[170:173], v[126:129]
	s_waitcnt lgkmcnt(5)
	v_mfma_f32_16x16x32_bf16 v[110:113], v[134:137], v[178:181], v[110:113]
	v_mfma_f32_16x16x32_bf16 v[106:109], v[146:149], v[178:181], v[106:109]
	s_waitcnt lgkmcnt(3)
	v_mfma_f32_16x16x32_bf16 v[94:97], v[134:137], v[186:189], v[94:97]
	v_mfma_f32_16x16x32_bf16 v[90:93], v[146:149], v[186:189], v[90:93]
	s_waitcnt lgkmcnt(1)
	v_mfma_f32_16x16x32_bf16 v[78:81], v[134:137], v[194:197], v[78:81]
	v_mfma_f32_16x16x32_bf16 v[74:77], v[146:149], v[194:197], v[74:77]
	v_mfma_f32_16x16x32_bf16 v[138:141], v[142:145], v[174:177], v[138:141]
	v_mfma_f32_16x16x32_bf16 v[126:129], v[150:153], v[174:177], v[126:129]
	v_mfma_f32_16x16x32_bf16 v[110:113], v[142:145], v[182:185], v[110:113]
	v_mfma_f32_16x16x32_bf16 v[106:109], v[150:153], v[182:185], v[106:109]
	v_mfma_f32_16x16x32_bf16 v[94:97], v[142:145], v[190:193], v[94:97]
	v_mfma_f32_16x16x32_bf16 v[90:93], v[150:153], v[190:193], v[90:93]
	s_waitcnt lgkmcnt(0)
	v_mfma_f32_16x16x32_bf16 v[78:81], v[142:145], v[198:201], v[78:81]
	v_mfma_f32_16x16x32_bf16 v[74:77], v[150:153], v[198:201], v[74:77]
	v_mfma_f32_16x16x32_bf16 v[118:121], v[154:157], v[170:173], v[118:121]
	v_mfma_f32_16x16x32_bf16 v[114:117], v[162:165], v[170:173], v[114:117]
	v_mfma_f32_16x16x32_bf16 v[102:105], v[154:157], v[178:181], v[102:105]
	v_mfma_f32_16x16x32_bf16 v[98:101], v[162:165], v[178:181], v[98:101]
	v_mfma_f32_16x16x32_bf16 v[86:89], v[154:157], v[186:189], v[86:89]
	v_mfma_f32_16x16x32_bf16 v[82:85], v[162:165], v[186:189], v[82:85]
	v_mfma_f32_16x16x32_bf16 v[70:73], v[154:157], v[194:197], v[70:73]
	v_mfma_f32_16x16x32_bf16 v[66:69], v[162:165], v[194:197], v[66:69]
	v_mfma_f32_16x16x32_bf16 v[118:121], v[158:161], v[174:177], v[118:121]
	v_mfma_f32_16x16x32_bf16 v[114:117], v[166:169], v[174:177], v[114:117]
	v_mfma_f32_16x16x32_bf16 v[102:105], v[158:161], v[182:185], v[102:105]
	v_mfma_f32_16x16x32_bf16 v[98:101], v[166:169], v[182:185], v[98:101]
	v_mfma_f32_16x16x32_bf16 v[86:89], v[158:161], v[190:193], v[86:89]
	v_mfma_f32_16x16x32_bf16 v[82:85], v[166:169], v[190:193], v[82:85]
	v_mfma_f32_16x16x32_bf16 v[70:73], v[158:161], v[198:201], v[70:73]
	v_mfma_f32_16x16x32_bf16 v[66:69], v[166:169], v[198:201], v[66:69]
	s_barrier
	ds_read_b128 v[170:173], v133 offset:16384
	ds_read_b128 v[174:177], v133 offset:17408
	ds_read_b128 v[178:181], v133 offset:18432
	ds_read_b128 v[182:185], v133 offset:19456
	ds_read_b128 v[186:189], v133 offset:20480
	ds_read_b128 v[190:193], v133 offset:21504
	ds_read_b128 v[194:197], v133 offset:22528
	ds_read_b128 v[198:201], v133 offset:23552
	s_mov_b32 m0, s33
	s_nop 0
	buffer_load_dwordx4 v130, s[8:11], s62 offen lds
	s_add_i32 s63, s62, 0x40000
	s_mov_b32 m0, s35
	s_nop 0
	buffer_load_dwordx4 v131, s[8:11], s62 offen lds
	s_nop 0
	s_mov_b32 m0, s36
	s_nop 0
	buffer_load_dwordx4 v130, s[8:11], s63 offen lds
	s_nop 0
	s_mov_b32 m0, s37
	s_nop 0
	buffer_load_dwordx4 v131, s[8:11], s63 offen lds
	s_nop 0
	s_mov_b32 m0, s31
	s_nop 0
	buffer_load_dwordx4 v130, s[12:15], s64 offen lds
	s_nop 0
	s_mov_b32 m0, s40
	s_nop 0
	buffer_load_dwordx4 v131, s[12:15], s64 offen lds
	s_waitcnt vmcnt(8)
	s_waitcnt lgkmcnt(0)
	s_barrier
	s_waitcnt lgkmcnt(7)
	v_mfma_f32_16x16x32_bf16 v[62:65], v[134:137], v[170:173], v[62:65]
	v_mfma_f32_16x16x32_bf16 v[58:61], v[146:149], v[170:173], v[58:61]
	s_waitcnt lgkmcnt(5)
	v_mfma_f32_16x16x32_bf16 v[46:49], v[134:137], v[178:181], v[46:49]
	v_mfma_f32_16x16x32_bf16 v[42:45], v[146:149], v[178:181], v[42:45]
	s_waitcnt lgkmcnt(3)
	v_mfma_f32_16x16x32_bf16 v[30:33], v[134:137], v[186:189], v[30:33]
	v_mfma_f32_16x16x32_bf16 v[26:29], v[146:149], v[186:189], v[26:29]
	s_waitcnt lgkmcnt(1)
	v_mfma_f32_16x16x32_bf16 v[14:17], v[134:137], v[194:197], v[14:17]
	v_mfma_f32_16x16x32_bf16 v[10:13], v[146:149], v[194:197], v[10:13]
	v_mfma_f32_16x16x32_bf16 v[62:65], v[142:145], v[174:177], v[62:65]
	v_mfma_f32_16x16x32_bf16 v[58:61], v[150:153], v[174:177], v[58:61]
	v_mfma_f32_16x16x32_bf16 v[46:49], v[142:145], v[182:185], v[46:49]
	v_mfma_f32_16x16x32_bf16 v[42:45], v[150:153], v[182:185], v[42:45]
	v_mfma_f32_16x16x32_bf16 v[30:33], v[142:145], v[190:193], v[30:33]
	v_mfma_f32_16x16x32_bf16 v[26:29], v[150:153], v[190:193], v[26:29]
	s_waitcnt lgkmcnt(0)
	v_mfma_f32_16x16x32_bf16 v[14:17], v[142:145], v[198:201], v[14:17]
	v_mfma_f32_16x16x32_bf16 v[10:13], v[150:153], v[198:201], v[10:13]
	v_mfma_f32_16x16x32_bf16 v[54:57], v[154:157], v[170:173], v[54:57]
	v_mfma_f32_16x16x32_bf16 v[50:53], v[162:165], v[170:173], v[50:53]
	v_mfma_f32_16x16x32_bf16 v[38:41], v[154:157], v[178:181], v[38:41]
	v_mfma_f32_16x16x32_bf16 v[34:37], v[162:165], v[178:181], v[34:37]
	v_mfma_f32_16x16x32_bf16 v[22:25], v[154:157], v[186:189], v[22:25]
	v_mfma_f32_16x16x32_bf16 v[18:21], v[162:165], v[186:189], v[18:21]
	v_mfma_f32_16x16x32_bf16 v[6:9], v[154:157], v[194:197], v[6:9]
	v_mfma_f32_16x16x32_bf16 v[2:5], v[162:165], v[194:197], v[2:5]
	v_mfma_f32_16x16x32_bf16 v[54:57], v[158:161], v[174:177], v[54:57]
	v_mfma_f32_16x16x32_bf16 v[50:53], v[166:169], v[174:177], v[50:53]
	v_mfma_f32_16x16x32_bf16 v[38:41], v[158:161], v[182:185], v[38:41]
	v_mfma_f32_16x16x32_bf16 v[34:37], v[166:169], v[182:185], v[34:37]
	v_mfma_f32_16x16x32_bf16 v[22:25], v[158:161], v[190:193], v[22:25]
	v_mfma_f32_16x16x32_bf16 v[18:21], v[166:169], v[190:193], v[18:21]
	v_mfma_f32_16x16x32_bf16 v[6:9], v[158:161], v[198:201], v[6:9]
	v_mfma_f32_16x16x32_bf16 v[2:5], v[166:169], v[198:201], v[2:5]
	s_barrier
	v_add_u32_e32 v150, 0x18000, v132
	v_add_u32_e32 v166, 0x1c000, v132
	ds_read_b128 v[134:137], v150
	ds_read_b128 v[142:145], v150 offset:1024
	ds_read_b128 v[146:149], v150 offset:2048
	ds_read_b128 v[150:153], v150 offset:3072
	ds_read_b128 v[154:157], v166
	ds_read_b128 v[158:161], v166 offset:1024
	ds_read_b128 v[162:165], v166 offset:2048
	ds_read_b128 v[166:169], v166 offset:3072
	ds_read_b128 v[170:173], v133 offset:32768
	ds_read_b128 v[174:177], v133 offset:33792
	ds_read_b128 v[178:181], v133 offset:34816
	ds_read_b128 v[182:185], v133 offset:35840
	ds_read_b128 v[186:189], v133 offset:36864
	ds_read_b128 v[190:193], v133 offset:37888
	ds_read_b128 v[194:197], v133 offset:38912
	ds_read_b128 v[198:201], v133 offset:39936
	s_add_i32 s63, s64, 0x40000
	s_mov_b32 m0, s41
	s_nop 0
	buffer_load_dwordx4 v130, s[12:15], s63 offen lds
	s_nop 0
	s_mov_b32 m0, s42
	s_nop 0
	buffer_load_dwordx4 v131, s[12:15], s63 offen lds
	s_waitcnt vmcnt(8)
	s_waitcnt lgkmcnt(0)
	s_barrier
	s_waitcnt lgkmcnt(7)
	v_mfma_f32_16x16x32_bf16 v[138:141], v[134:137], v[170:173], v[138:141]
	v_mfma_f32_16x16x32_bf16 v[126:129], v[146:149], v[170:173], v[126:129]
	s_waitcnt lgkmcnt(5)
	v_mfma_f32_16x16x32_bf16 v[110:113], v[134:137], v[178:181], v[110:113]
	v_mfma_f32_16x16x32_bf16 v[106:109], v[146:149], v[178:181], v[106:109]
	s_waitcnt lgkmcnt(3)
	v_mfma_f32_16x16x32_bf16 v[94:97], v[134:137], v[186:189], v[94:97]
	v_mfma_f32_16x16x32_bf16 v[90:93], v[146:149], v[186:189], v[90:93]
	s_waitcnt lgkmcnt(1)
	v_mfma_f32_16x16x32_bf16 v[78:81], v[134:137], v[194:197], v[78:81]
	v_mfma_f32_16x16x32_bf16 v[74:77], v[146:149], v[194:197], v[74:77]
	v_mfma_f32_16x16x32_bf16 v[138:141], v[142:145], v[174:177], v[138:141]
	v_mfma_f32_16x16x32_bf16 v[126:129], v[150:153], v[174:177], v[126:129]
	v_mfma_f32_16x16x32_bf16 v[110:113], v[142:145], v[182:185], v[110:113]
	v_mfma_f32_16x16x32_bf16 v[106:109], v[150:153], v[182:185], v[106:109]
	v_mfma_f32_16x16x32_bf16 v[94:97], v[142:145], v[190:193], v[94:97]
	v_mfma_f32_16x16x32_bf16 v[90:93], v[150:153], v[190:193], v[90:93]
	s_waitcnt lgkmcnt(0)
	v_mfma_f32_16x16x32_bf16 v[78:81], v[142:145], v[198:201], v[78:81]
	v_mfma_f32_16x16x32_bf16 v[74:77], v[150:153], v[198:201], v[74:77]
	v_mfma_f32_16x16x32_bf16 v[118:121], v[154:157], v[170:173], v[118:121]
	v_mfma_f32_16x16x32_bf16 v[114:117], v[162:165], v[170:173], v[114:117]
	v_mfma_f32_16x16x32_bf16 v[102:105], v[154:157], v[178:181], v[102:105]
	v_mfma_f32_16x16x32_bf16 v[98:101], v[162:165], v[178:181], v[98:101]
	v_mfma_f32_16x16x32_bf16 v[86:89], v[154:157], v[186:189], v[86:89]
	v_mfma_f32_16x16x32_bf16 v[82:85], v[162:165], v[186:189], v[82:85]
	v_mfma_f32_16x16x32_bf16 v[70:73], v[154:157], v[194:197], v[70:73]
	v_mfma_f32_16x16x32_bf16 v[66:69], v[162:165], v[194:197], v[66:69]
	v_mfma_f32_16x16x32_bf16 v[118:121], v[158:161], v[174:177], v[118:121]
	v_mfma_f32_16x16x32_bf16 v[114:117], v[166:169], v[174:177], v[114:117]
	v_mfma_f32_16x16x32_bf16 v[102:105], v[158:161], v[182:185], v[102:105]
	v_mfma_f32_16x16x32_bf16 v[98:101], v[166:169], v[182:185], v[98:101]
	v_mfma_f32_16x16x32_bf16 v[86:89], v[158:161], v[190:193], v[86:89]
	v_mfma_f32_16x16x32_bf16 v[82:85], v[166:169], v[190:193], v[82:85]
	v_mfma_f32_16x16x32_bf16 v[70:73], v[158:161], v[198:201], v[70:73]
	v_mfma_f32_16x16x32_bf16 v[66:69], v[166:169], v[198:201], v[66:69]
	s_barrier
	ds_read_b128 v[170:173], v133 offset:49152
	ds_read_b128 v[174:177], v133 offset:50176
	ds_read_b128 v[178:181], v133 offset:51200
	ds_read_b128 v[182:185], v133 offset:52224
	ds_read_b128 v[186:189], v133 offset:53248
	ds_read_b128 v[190:193], v133 offset:54272
	ds_read_b128 v[194:197], v133 offset:55296
	ds_read_b128 v[198:201], v133 offset:56320
	s_or_b32 s63, s62, 0x80
	s_mov_b32 m0, s43
	s_nop 0
	buffer_load_dwordx4 v130, s[8:11], s63 offen lds
	s_add_i32 s62, s62, 0x40080
	s_mov_b32 m0, s44
	s_nop 0
	buffer_load_dwordx4 v131, s[8:11], s63 offen lds
	s_nop 0
	s_mov_b32 m0, s47
	s_nop 0
	buffer_load_dwordx4 v130, s[8:11], s62 offen lds
	s_nop 0
	s_mov_b32 m0, s48
	s_nop 0
	buffer_load_dwordx4 v131, s[8:11], s62 offen lds
	s_nop 0
	s_mov_b32 m0, s45
	s_nop 0
	buffer_load_dwordx4 v130, s[12:15], s61 offen lds
	s_nop 0
	s_mov_b32 m0, s46
	s_nop 0
	buffer_load_dwordx4 v131, s[12:15], s61 offen lds
	s_waitcnt vmcnt(8)
	s_waitcnt lgkmcnt(0)
	s_barrier
	s_waitcnt lgkmcnt(7)
	v_mfma_f32_16x16x32_bf16 v[62:65], v[134:137], v[170:173], v[62:65]
	v_mfma_f32_16x16x32_bf16 v[58:61], v[146:149], v[170:173], v[58:61]
	s_waitcnt lgkmcnt(5)
	v_mfma_f32_16x16x32_bf16 v[46:49], v[134:137], v[178:181], v[46:49]
	v_mfma_f32_16x16x32_bf16 v[42:45], v[146:149], v[178:181], v[42:45]
	s_waitcnt lgkmcnt(3)
	v_mfma_f32_16x16x32_bf16 v[30:33], v[134:137], v[186:189], v[30:33]
	v_mfma_f32_16x16x32_bf16 v[26:29], v[146:149], v[186:189], v[26:29]
	s_waitcnt lgkmcnt(1)
	v_mfma_f32_16x16x32_bf16 v[14:17], v[134:137], v[194:197], v[14:17]
	v_mfma_f32_16x16x32_bf16 v[10:13], v[146:149], v[194:197], v[10:13]
	v_mfma_f32_16x16x32_bf16 v[62:65], v[142:145], v[174:177], v[62:65]
	v_mfma_f32_16x16x32_bf16 v[58:61], v[150:153], v[174:177], v[58:61]
	v_mfma_f32_16x16x32_bf16 v[46:49], v[142:145], v[182:185], v[46:49]
	v_mfma_f32_16x16x32_bf16 v[42:45], v[150:153], v[182:185], v[42:45]
	v_mfma_f32_16x16x32_bf16 v[30:33], v[142:145], v[190:193], v[30:33]
	v_mfma_f32_16x16x32_bf16 v[26:29], v[150:153], v[190:193], v[26:29]
	s_waitcnt lgkmcnt(0)
	v_mfma_f32_16x16x32_bf16 v[14:17], v[142:145], v[198:201], v[14:17]
	v_mfma_f32_16x16x32_bf16 v[10:13], v[150:153], v[198:201], v[10:13]
	v_mfma_f32_16x16x32_bf16 v[54:57], v[154:157], v[170:173], v[54:57]
	v_mfma_f32_16x16x32_bf16 v[50:53], v[162:165], v[170:173], v[50:53]
	v_mfma_f32_16x16x32_bf16 v[38:41], v[154:157], v[178:181], v[38:41]
	v_mfma_f32_16x16x32_bf16 v[34:37], v[162:165], v[178:181], v[34:37]
	v_mfma_f32_16x16x32_bf16 v[22:25], v[154:157], v[186:189], v[22:25]
	v_mfma_f32_16x16x32_bf16 v[18:21], v[162:165], v[186:189], v[18:21]
	v_mfma_f32_16x16x32_bf16 v[6:9], v[154:157], v[194:197], v[6:9]
	v_mfma_f32_16x16x32_bf16 v[2:5], v[162:165], v[194:197], v[2:5]
	v_mfma_f32_16x16x32_bf16 v[54:57], v[158:161], v[174:177], v[54:57]
	v_mfma_f32_16x16x32_bf16 v[50:53], v[166:169], v[174:177], v[50:53]
	v_mfma_f32_16x16x32_bf16 v[38:41], v[158:161], v[182:185], v[38:41]
	v_mfma_f32_16x16x32_bf16 v[34:37], v[166:169], v[182:185], v[34:37]
	v_mfma_f32_16x16x32_bf16 v[22:25], v[158:161], v[190:193], v[22:25]
	v_mfma_f32_16x16x32_bf16 v[18:21], v[166:169], v[190:193], v[18:21]
	v_mfma_f32_16x16x32_bf16 v[6:9], v[158:161], v[198:201], v[6:9]
	v_mfma_f32_16x16x32_bf16 v[2:5], v[166:169], v[198:201], v[2:5]
	s_barrier
	s_add_i32 s59, s59, 2
	s_addk_i32 s60, 0x100
	s_cmp_gt_u32 s59, 13
	s_cbranch_scc0 .LBB0_223
	s_andn2_b64 vcc, exec, s[6:7]
	s_cbranch_vccnz .LBB0_215
	v_mov_b32_e32 v2, 0
	s_mov_b32 s18, s52
	s_mov_b32 s29, s53
	s_mov_b32 s34, s3
	s_mov_b32 s39, s2
	s_mov_b32 s51, s54
	v_mov_b32_e32 v3, v2
	v_mov_b32_e32 v4, v2
	v_mov_b32_e32 v5, v2
	v_mov_b32_e32 v6, v2
	v_mov_b32_e32 v7, v2
	v_mov_b32_e32 v8, v2
	v_mov_b32_e32 v9, v2
	v_mov_b32_e32 v18, v2
	v_mov_b32_e32 v19, v2
	v_mov_b32_e32 v20, v2
	v_mov_b32_e32 v21, v2
	v_mov_b32_e32 v22, v2
	v_mov_b32_e32 v23, v2
	v_mov_b32_e32 v24, v2
	v_mov_b32_e32 v25, v2
	v_mov_b32_e32 v34, v2
	v_mov_b32_e32 v35, v2
	v_mov_b32_e32 v36, v2
	v_mov_b32_e32 v37, v2
	v_mov_b32_e32 v38, v2
	v_mov_b32_e32 v39, v2
	v_mov_b32_e32 v40, v2
	v_mov_b32_e32 v41, v2
	v_mov_b32_e32 v50, v2
	v_mov_b32_e32 v51, v2
	v_mov_b32_e32 v52, v2
	v_mov_b32_e32 v53, v2
	v_mov_b32_e32 v54, v2
	v_mov_b32_e32 v55, v2
	v_mov_b32_e32 v56, v2
	v_mov_b32_e32 v57, v2
	v_mov_b32_e32 v10, v2
	v_mov_b32_e32 v11, v2
	v_mov_b32_e32 v12, v2
	v_mov_b32_e32 v13, v2
	v_mov_b32_e32 v14, v2
	v_mov_b32_e32 v15, v2
	v_mov_b32_e32 v16, v2
	v_mov_b32_e32 v17, v2
	v_mov_b32_e32 v26, v2
	v_mov_b32_e32 v27, v2
	v_mov_b32_e32 v28, v2
	v_mov_b32_e32 v29, v2
	v_mov_b32_e32 v30, v2
	v_mov_b32_e32 v31, v2
	v_mov_b32_e32 v32, v2
	v_mov_b32_e32 v33, v2
	v_mov_b32_e32 v42, v2
	v_mov_b32_e32 v43, v2
	v_mov_b32_e32 v44, v2
	v_mov_b32_e32 v45, v2
	v_mov_b32_e32 v46, v2
	v_mov_b32_e32 v47, v2
	v_mov_b32_e32 v48, v2
	v_mov_b32_e32 v49, v2
	v_mov_b32_e32 v58, v2
	v_mov_b32_e32 v59, v2
	v_mov_b32_e32 v60, v2
	v_mov_b32_e32 v61, v2
	v_mov_b32_e32 v62, v2
	v_mov_b32_e32 v63, v2
	v_mov_b32_e32 v64, v2
	v_mov_b32_e32 v65, v2
	v_mov_b32_e32 v66, v2
	v_mov_b32_e32 v67, v2
	v_mov_b32_e32 v68, v2
	v_mov_b32_e32 v69, v2
	v_mov_b32_e32 v70, v2
	v_mov_b32_e32 v71, v2
	v_mov_b32_e32 v72, v2
	v_mov_b32_e32 v73, v2
	v_mov_b32_e32 v82, v2
	v_mov_b32_e32 v83, v2
	v_mov_b32_e32 v84, v2
	v_mov_b32_e32 v85, v2
	v_mov_b32_e32 v86, v2
	v_mov_b32_e32 v87, v2
	v_mov_b32_e32 v88, v2
	v_mov_b32_e32 v89, v2
	v_mov_b32_e32 v98, v2
	v_mov_b32_e32 v99, v2
	v_mov_b32_e32 v100, v2
	v_mov_b32_e32 v101, v2
	v_mov_b32_e32 v102, v2
	v_mov_b32_e32 v103, v2
	v_mov_b32_e32 v104, v2
	v_mov_b32_e32 v105, v2
	v_mov_b32_e32 v114, v2
	v_mov_b32_e32 v115, v2
	v_mov_b32_e32 v116, v2
	v_mov_b32_e32 v117, v2
	v_mov_b32_e32 v118, v2
	v_mov_b32_e32 v119, v2
	v_mov_b32_e32 v120, v2
	v_mov_b32_e32 v121, v2
	v_mov_b32_e32 v74, v2
	v_mov_b32_e32 v75, v2
	v_mov_b32_e32 v76, v2
	v_mov_b32_e32 v77, v2
	v_mov_b32_e32 v78, v2
	v_mov_b32_e32 v79, v2
	v_mov_b32_e32 v80, v2
	v_mov_b32_e32 v81, v2
	v_mov_b32_e32 v90, v2
	v_mov_b32_e32 v91, v2
	v_mov_b32_e32 v92, v2
	v_mov_b32_e32 v93, v2
	v_mov_b32_e32 v94, v2
	v_mov_b32_e32 v95, v2
	v_mov_b32_e32 v96, v2
	v_mov_b32_e32 v97, v2
	v_mov_b32_e32 v106, v2
	v_mov_b32_e32 v107, v2
	v_mov_b32_e32 v108, v2
	v_mov_b32_e32 v109, v2
	v_mov_b32_e32 v110, v2
	v_mov_b32_e32 v111, v2
	v_mov_b32_e32 v112, v2
	v_mov_b32_e32 v113, v2
	v_mov_b32_e32 v126, v2
	v_mov_b32_e32 v127, v2
	v_mov_b32_e32 v128, v2
	v_mov_b32_e32 v129, v2
	v_mov_b32_e32 v138, v2
	v_mov_b32_e32 v139, v2
	v_mov_b32_e32 v140, v2
	v_mov_b32_e32 v141, v2
	s_branch .LBB0_215

.LBB0_353:
	ds_read_b128 v[136:139], v153
	ds_read_b128 v[140:143], v153 offset:1024
	ds_read_b128 v[158:161], v153 offset:2048
	ds_read_b128 v[162:165], v153 offset:3072
	ds_read_b128 v[166:169], v154
	ds_read_b128 v[170:173], v154 offset:1024
	ds_read_b128 v[174:177], v154 offset:2048
	ds_read_b128 v[178:181], v154 offset:3072
	s_add_i32 s66, s63, 0xfffe0080
	s_cmp_eq_u32 s65, 4
	s_cselect_b32 s68, s1, s66
	s_cselect_b32 s67, s62, s64
	s_or_b32 s66, s68, 0x80
	ds_read_b128 v[182:185], v155
	ds_read_b128 v[186:189], v155 offset:1024
	ds_read_b128 v[190:193], v155 offset:2048
	ds_read_b128 v[194:197], v155 offset:3072
	ds_read_b128 v[198:201], v155 offset:4096
	ds_read_b128 v[202:205], v155 offset:5120
	ds_read_b128 v[206:209], v155 offset:6144
	ds_read_b128 v[210:213], v155 offset:7168
	s_mov_b32 m0, s48
	s_nop 0
	buffer_load_dwordx4 v147, s[12:15], s63 offen lds
	s_nop 0
	s_mov_b32 m0, s49
	s_nop 0
	buffer_load_dwordx4 v148, s[12:15], s63 offen lds
	s_waitcnt vmcnt(8)
	s_waitcnt lgkmcnt(0)
	s_barrier
	s_waitcnt lgkmcnt(0)
	v_mfma_i32_16x16x64_i8 v[126:129], v[136:139], v[182:185], v[126:129]
	v_mfma_i32_16x16x64_i8 v[122:125], v[158:161], v[182:185], v[122:125]
	v_mfma_i32_16x16x64_i8 v[118:121], v[136:139], v[190:193], v[118:121]
	v_mfma_i32_16x16x64_i8 v[114:117], v[158:161], v[190:193], v[114:117]
	v_mfma_i32_16x16x64_i8 v[110:113], v[136:139], v[198:201], v[110:113]
	v_mfma_i32_16x16x64_i8 v[106:109], v[158:161], v[198:201], v[106:109]
	v_mfma_i32_16x16x64_i8 v[102:105], v[136:139], v[206:209], v[102:105]
	v_mfma_i32_16x16x64_i8 v[98:101], v[158:161], v[206:209], v[98:101]
	v_mfma_i32_16x16x64_i8 v[126:129], v[140:143], v[186:189], v[126:129]
	v_mfma_i32_16x16x64_i8 v[122:125], v[162:165], v[186:189], v[122:125]
	v_mfma_i32_16x16x64_i8 v[118:121], v[140:143], v[194:197], v[118:121]
	v_mfma_i32_16x16x64_i8 v[114:117], v[162:165], v[194:197], v[114:117]
	v_mfma_i32_16x16x64_i8 v[110:113], v[140:143], v[202:205], v[110:113]
	v_mfma_i32_16x16x64_i8 v[106:109], v[162:165], v[202:205], v[106:109]
	v_mfma_i32_16x16x64_i8 v[102:105], v[140:143], v[210:213], v[102:105]
	v_mfma_i32_16x16x64_i8 v[98:101], v[162:165], v[210:213], v[98:101]
	v_mfma_i32_16x16x64_i8 v[94:97], v[166:169], v[182:185], v[94:97]
	v_mfma_i32_16x16x64_i8 v[90:93], v[174:177], v[182:185], v[90:93]
	v_mfma_i32_16x16x64_i8 v[86:89], v[166:169], v[190:193], v[86:89]
	v_mfma_i32_16x16x64_i8 v[82:85], v[174:177], v[190:193], v[82:85]
	v_mfma_i32_16x16x64_i8 v[78:81], v[166:169], v[198:201], v[78:81]
	v_mfma_i32_16x16x64_i8 v[74:77], v[174:177], v[198:201], v[74:77]
	v_mfma_i32_16x16x64_i8 v[70:73], v[166:169], v[206:209], v[70:73]
	v_mfma_i32_16x16x64_i8 v[66:69], v[174:177], v[206:209], v[66:69]
	v_mfma_i32_16x16x64_i8 v[94:97], v[170:173], v[186:189], v[94:97]
	v_mfma_i32_16x16x64_i8 v[90:93], v[178:181], v[186:189], v[90:93]
	v_mfma_i32_16x16x64_i8 v[86:89], v[170:173], v[194:197], v[86:89]
	v_mfma_i32_16x16x64_i8 v[82:85], v[178:181], v[194:197], v[82:85]
	v_mfma_i32_16x16x64_i8 v[78:81], v[170:173], v[202:205], v[78:81]
	v_mfma_i32_16x16x64_i8 v[74:77], v[178:181], v[202:205], v[74:77]
	v_mfma_i32_16x16x64_i8 v[70:73], v[170:173], v[210:213], v[70:73]
	v_mfma_i32_16x16x64_i8 v[66:69], v[178:181], v[210:213], v[66:69]
	s_barrier
	ds_read_b128 v[182:185], v155 offset:16384
	ds_read_b128 v[186:189], v155 offset:17408
	ds_read_b128 v[190:193], v155 offset:18432
	ds_read_b128 v[194:197], v155 offset:19456
	ds_read_b128 v[198:201], v155 offset:20480
	ds_read_b128 v[202:205], v155 offset:21504
	ds_read_b128 v[206:209], v155 offset:22528
	ds_read_b128 v[210:213], v155 offset:23552
	s_mov_b32 m0, s34
	s_nop 0
	buffer_load_dwordx4 v145, s[8:11], s67 offen lds
	s_add_i32 s69, s67, 0x20000
	s_mov_b32 m0, s35
	s_nop 0
	buffer_load_dwordx4 v146, s[8:11], s67 offen lds
	s_nop 0
	s_mov_b32 m0, s36
	s_nop 0
	buffer_load_dwordx4 v145, s[8:11], s69 offen lds
	s_nop 0
	s_mov_b32 m0, s37
	s_nop 0
	buffer_load_dwordx4 v146, s[8:11], s69 offen lds
	s_nop 0
	s_mov_b32 m0, s33
	s_nop 0
	buffer_load_dwordx4 v147, s[12:15], s68 offen lds
	s_nop 0
	s_mov_b32 m0, s2
	s_nop 0
	buffer_load_dwordx4 v148, s[12:15], s68 offen lds
	s_waitcnt vmcnt(8)
	s_waitcnt lgkmcnt(0)
	s_barrier
	s_waitcnt lgkmcnt(0)
	v_mfma_i32_16x16x64_i8 v[62:65], v[136:139], v[182:185], v[62:65]
	v_mfma_i32_16x16x64_i8 v[58:61], v[158:161], v[182:185], v[58:61]
	v_mfma_i32_16x16x64_i8 v[54:57], v[136:139], v[190:193], v[54:57]
	v_mfma_i32_16x16x64_i8 v[50:53], v[158:161], v[190:193], v[50:53]
	v_mfma_i32_16x16x64_i8 v[46:49], v[136:139], v[198:201], v[46:49]
	v_mfma_i32_16x16x64_i8 v[42:45], v[158:161], v[198:201], v[42:45]
	v_mfma_i32_16x16x64_i8 v[38:41], v[136:139], v[206:209], v[38:41]
	v_mfma_i32_16x16x64_i8 v[34:37], v[158:161], v[206:209], v[34:37]
	v_mfma_i32_16x16x64_i8 v[62:65], v[140:143], v[186:189], v[62:65]
	v_mfma_i32_16x16x64_i8 v[58:61], v[162:165], v[186:189], v[58:61]
	v_mfma_i32_16x16x64_i8 v[54:57], v[140:143], v[194:197], v[54:57]
	v_mfma_i32_16x16x64_i8 v[50:53], v[162:165], v[194:197], v[50:53]
	v_mfma_i32_16x16x64_i8 v[46:49], v[140:143], v[202:205], v[46:49]
	v_mfma_i32_16x16x64_i8 v[42:45], v[162:165], v[202:205], v[42:45]
	v_mfma_i32_16x16x64_i8 v[38:41], v[140:143], v[210:213], v[38:41]
	v_mfma_i32_16x16x64_i8 v[34:37], v[162:165], v[210:213], v[34:37]
	v_mfma_i32_16x16x64_i8 v[30:33], v[166:169], v[182:185], v[30:33]
	v_mfma_i32_16x16x64_i8 v[26:29], v[174:177], v[182:185], v[26:29]
	v_mfma_i32_16x16x64_i8 v[22:25], v[166:169], v[190:193], v[22:25]
	v_mfma_i32_16x16x64_i8 v[18:21], v[174:177], v[190:193], v[18:21]
	v_mfma_i32_16x16x64_i8 v[14:17], v[166:169], v[198:201], v[14:17]
	v_mfma_i32_16x16x64_i8 v[10:13], v[174:177], v[198:201], v[10:13]
	v_mfma_i32_16x16x64_i8 v[6:9], v[166:169], v[206:209], v[6:9]
	v_mfma_i32_16x16x64_i8 v[2:5], v[174:177], v[206:209], v[2:5]
	v_mfma_i32_16x16x64_i8 v[30:33], v[170:173], v[186:189], v[30:33]
	v_mfma_i32_16x16x64_i8 v[26:29], v[178:181], v[186:189], v[26:29]
	v_mfma_i32_16x16x64_i8 v[22:25], v[170:173], v[194:197], v[22:25]
	v_mfma_i32_16x16x64_i8 v[18:21], v[178:181], v[194:197], v[18:21]
	v_mfma_i32_16x16x64_i8 v[14:17], v[170:173], v[202:205], v[14:17]
	v_mfma_i32_16x16x64_i8 v[10:13], v[178:181], v[202:205], v[10:13]
	v_mfma_i32_16x16x64_i8 v[6:9], v[170:173], v[210:213], v[6:9]
	v_mfma_i32_16x16x64_i8 v[2:5], v[178:181], v[210:213], v[2:5]
	s_barrier
	ds_read_b128 v[136:139], v156
	ds_read_b128 v[140:143], v156 offset:1024
	ds_read_b128 v[158:161], v156 offset:2048
	ds_read_b128 v[162:165], v156 offset:3072
	ds_read_b128 v[166:169], v157
	ds_read_b128 v[170:173], v157 offset:1024
	ds_read_b128 v[174:177], v157 offset:2048
	ds_read_b128 v[178:181], v157 offset:3072
	ds_read_b128 v[182:185], v155 offset:32768
	ds_read_b128 v[186:189], v155 offset:33792
	ds_read_b128 v[190:193], v155 offset:34816
	ds_read_b128 v[194:197], v155 offset:35840
	ds_read_b128 v[198:201], v155 offset:36864
	ds_read_b128 v[202:205], v155 offset:37888
	ds_read_b128 v[206:209], v155 offset:38912
	ds_read_b128 v[210:213], v155 offset:39936
	s_add_i32 s68, s68, 0x20000
	s_mov_b32 m0, s3
	s_nop 0
	buffer_load_dwordx4 v147, s[12:15], s68 offen lds
	s_nop 0
	s_mov_b32 m0, s38
	s_nop 0
	buffer_load_dwordx4 v148, s[12:15], s68 offen lds
	s_waitcnt vmcnt(8)
	s_waitcnt lgkmcnt(0)
	s_barrier
	s_waitcnt lgkmcnt(0)
	v_mfma_i32_16x16x64_i8 v[126:129], v[136:139], v[182:185], v[126:129]
	v_mfma_i32_16x16x64_i8 v[122:125], v[158:161], v[182:185], v[122:125]
	v_mfma_i32_16x16x64_i8 v[118:121], v[136:139], v[190:193], v[118:121]
	v_mfma_i32_16x16x64_i8 v[114:117], v[158:161], v[190:193], v[114:117]
	v_mfma_i32_16x16x64_i8 v[110:113], v[136:139], v[198:201], v[110:113]
	v_mfma_i32_16x16x64_i8 v[106:109], v[158:161], v[198:201], v[106:109]
	v_mfma_i32_16x16x64_i8 v[102:105], v[136:139], v[206:209], v[102:105]
	v_mfma_i32_16x16x64_i8 v[98:101], v[158:161], v[206:209], v[98:101]
	v_mfma_i32_16x16x64_i8 v[126:129], v[140:143], v[186:189], v[126:129]
	v_mfma_i32_16x16x64_i8 v[122:125], v[162:165], v[186:189], v[122:125]
	v_mfma_i32_16x16x64_i8 v[118:121], v[140:143], v[194:197], v[118:121]
	v_mfma_i32_16x16x64_i8 v[114:117], v[162:165], v[194:197], v[114:117]
	v_mfma_i32_16x16x64_i8 v[110:113], v[140:143], v[202:205], v[110:113]
	v_mfma_i32_16x16x64_i8 v[106:109], v[162:165], v[202:205], v[106:109]
	v_mfma_i32_16x16x64_i8 v[102:105], v[140:143], v[210:213], v[102:105]
	v_mfma_i32_16x16x64_i8 v[98:101], v[162:165], v[210:213], v[98:101]
	v_mfma_i32_16x16x64_i8 v[94:97], v[166:169], v[182:185], v[94:97]
	v_mfma_i32_16x16x64_i8 v[90:93], v[174:177], v[182:185], v[90:93]
	v_mfma_i32_16x16x64_i8 v[86:89], v[166:169], v[190:193], v[86:89]
	v_mfma_i32_16x16x64_i8 v[82:85], v[174:177], v[190:193], v[82:85]
	v_mfma_i32_16x16x64_i8 v[78:81], v[166:169], v[198:201], v[78:81]
	v_mfma_i32_16x16x64_i8 v[74:77], v[174:177], v[198:201], v[74:77]
	v_mfma_i32_16x16x64_i8 v[70:73], v[166:169], v[206:209], v[70:73]
	v_mfma_i32_16x16x64_i8 v[66:69], v[174:177], v[206:209], v[66:69]
	v_mfma_i32_16x16x64_i8 v[94:97], v[170:173], v[186:189], v[94:97]
	v_mfma_i32_16x16x64_i8 v[90:93], v[178:181], v[186:189], v[90:93]
	v_mfma_i32_16x16x64_i8 v[86:89], v[170:173], v[194:197], v[86:89]
	v_mfma_i32_16x16x64_i8 v[82:85], v[178:181], v[194:197], v[82:85]
	v_mfma_i32_16x16x64_i8 v[78:81], v[170:173], v[202:205], v[78:81]
	v_mfma_i32_16x16x64_i8 v[74:77], v[178:181], v[202:205], v[74:77]
	v_mfma_i32_16x16x64_i8 v[70:73], v[170:173], v[210:213], v[70:73]
	v_mfma_i32_16x16x64_i8 v[66:69], v[178:181], v[210:213], v[66:69]
	s_barrier
	ds_read_b128 v[182:185], v155 offset:49152
	ds_read_b128 v[186:189], v155 offset:50176
	ds_read_b128 v[190:193], v155 offset:51200
	ds_read_b128 v[194:197], v155 offset:52224
	ds_read_b128 v[198:201], v155 offset:53248
	ds_read_b128 v[202:205], v155 offset:54272
	ds_read_b128 v[206:209], v155 offset:55296
	ds_read_b128 v[210:213], v155 offset:56320
	s_or_b32 s68, s67, 0x80
	s_mov_b32 m0, s41
	s_nop 0
	buffer_load_dwordx4 v145, s[8:11], s68 offen lds
	s_add_i32 s67, s67, 0x20080
	s_mov_b32 m0, s42
	s_nop 0
	buffer_load_dwordx4 v146, s[8:11], s68 offen lds
	s_nop 0
	s_mov_b32 m0, s45
	s_nop 0
	buffer_load_dwordx4 v145, s[8:11], s67 offen lds
	s_nop 0
	s_mov_b32 m0, s46
	s_nop 0
	buffer_load_dwordx4 v146, s[8:11], s67 offen lds
	s_nop 0
	s_mov_b32 m0, s43
	s_nop 0
	buffer_load_dwordx4 v147, s[12:15], s66 offen lds
	s_nop 0
	s_mov_b32 m0, s44
	s_nop 0
	buffer_load_dwordx4 v148, s[12:15], s66 offen lds
	s_waitcnt vmcnt(8)
	s_waitcnt lgkmcnt(0)
	s_barrier
	s_waitcnt lgkmcnt(0)
	v_mfma_i32_16x16x64_i8 v[62:65], v[136:139], v[182:185], v[62:65]
	v_mfma_i32_16x16x64_i8 v[58:61], v[158:161], v[182:185], v[58:61]
	v_mfma_i32_16x16x64_i8 v[54:57], v[136:139], v[190:193], v[54:57]
	v_mfma_i32_16x16x64_i8 v[50:53], v[158:161], v[190:193], v[50:53]
	v_mfma_i32_16x16x64_i8 v[46:49], v[136:139], v[198:201], v[46:49]
	v_mfma_i32_16x16x64_i8 v[42:45], v[158:161], v[198:201], v[42:45]
	v_mfma_i32_16x16x64_i8 v[38:41], v[136:139], v[206:209], v[38:41]
	v_mfma_i32_16x16x64_i8 v[34:37], v[158:161], v[206:209], v[34:37]
	v_mfma_i32_16x16x64_i8 v[62:65], v[140:143], v[186:189], v[62:65]
	v_mfma_i32_16x16x64_i8 v[58:61], v[162:165], v[186:189], v[58:61]
	v_mfma_i32_16x16x64_i8 v[54:57], v[140:143], v[194:197], v[54:57]
	v_mfma_i32_16x16x64_i8 v[50:53], v[162:165], v[194:197], v[50:53]
	v_mfma_i32_16x16x64_i8 v[46:49], v[140:143], v[202:205], v[46:49]
	v_mfma_i32_16x16x64_i8 v[42:45], v[162:165], v[202:205], v[42:45]
	v_mfma_i32_16x16x64_i8 v[38:41], v[140:143], v[210:213], v[38:41]
	v_mfma_i32_16x16x64_i8 v[34:37], v[162:165], v[210:213], v[34:37]
	v_mfma_i32_16x16x64_i8 v[30:33], v[166:169], v[182:185], v[30:33]
	v_mfma_i32_16x16x64_i8 v[26:29], v[174:177], v[182:185], v[26:29]
	v_mfma_i32_16x16x64_i8 v[22:25], v[166:169], v[190:193], v[22:25]
	v_mfma_i32_16x16x64_i8 v[18:21], v[174:177], v[190:193], v[18:21]
	v_mfma_i32_16x16x64_i8 v[14:17], v[166:169], v[198:201], v[14:17]
	v_mfma_i32_16x16x64_i8 v[10:13], v[174:177], v[198:201], v[10:13]
	v_mfma_i32_16x16x64_i8 v[6:9], v[166:169], v[206:209], v[6:9]
	v_mfma_i32_16x16x64_i8 v[2:5], v[174:177], v[206:209], v[2:5]
	v_mfma_i32_16x16x64_i8 v[30:33], v[170:173], v[186:189], v[30:33]
	v_mfma_i32_16x16x64_i8 v[26:29], v[178:181], v[186:189], v[26:29]
	v_mfma_i32_16x16x64_i8 v[22:25], v[170:173], v[194:197], v[22:25]
	v_mfma_i32_16x16x64_i8 v[18:21], v[178:181], v[194:197], v[18:21]
	v_mfma_i32_16x16x64_i8 v[14:17], v[170:173], v[202:205], v[14:17]
	v_mfma_i32_16x16x64_i8 v[10:13], v[178:181], v[202:205], v[10:13]
	v_mfma_i32_16x16x64_i8 v[6:9], v[170:173], v[210:213], v[6:9]
	v_mfma_i32_16x16x64_i8 v[2:5], v[178:181], v[210:213], v[2:5]
	s_barrier
	s_add_i32 s65, s65, 2
	s_addk_i32 s63, 0x100
	s_addk_i32 s64, 0x100
	s_cmp_gt_u32 s65, 5
	s_cbranch_scc0 .LBB0_353
	s_and_b64 vcc, exec, s[24:25]
	s_cbranch_vccz .LBB0_356
	s_barrier

.LBB0_467:
	v_add_u32_e32 v147, 0x10000, v132
	ds_read_b128 v[138:141], v147
	ds_read_b128 v[142:145], v147 offset:1024
	ds_read_b128 v[148:151], v147 offset:2048
	ds_read_b128 v[152:155], v147 offset:3072
	v_add_u32_e32 v147, 0x14000, v132
	ds_read_b128 v[156:159], v147
	ds_read_b128 v[160:163], v147 offset:1024
	ds_read_b128 v[164:167], v147 offset:2048
	ds_read_b128 v[168:171], v147 offset:3072
	s_add_i32 s59, s3, s1
	s_add_i32 s58, s33, s1
	s_add_i32 s55, s59, 0x1600
	s_addk_i32 s58, 0x1600
	s_cmp_eq_u32 s1, 0
	s_cselect_b32 s60, s53, s55
	s_cselect_b32 s58, s54, s58
	s_add_i32 s55, s60, 0x80
	ds_read_b128 v[172:175], v133
	ds_read_b128 v[176:179], v133 offset:1024
	ds_read_b128 v[180:183], v133 offset:2048
	ds_read_b128 v[184:187], v133 offset:3072
	ds_read_b128 v[188:191], v133 offset:4096
	ds_read_b128 v[192:195], v133 offset:5120
	ds_read_b128 v[196:199], v133 offset:6144
	ds_read_b128 v[200:203], v133 offset:7168
	s_add_i32 s59, s59, 0xb1580
	s_mov_b32 m0, s46
	s_nop 0
	buffer_load_dwordx4 v130, s[12:15], s59 offen lds
	s_nop 0
	s_mov_b32 m0, s47
	s_nop 0
	buffer_load_dwordx4 v131, s[12:15], s59 offen lds
	s_waitcnt vmcnt(8)
	s_waitcnt lgkmcnt(0)
	s_barrier
	s_waitcnt lgkmcnt(7)
	v_mfma_f32_16x16x32_bf16 v[134:137], v[138:141], v[172:175], v[134:137]
	v_mfma_f32_16x16x32_bf16 v[122:125], v[148:151], v[172:175], v[122:125]
	s_waitcnt lgkmcnt(5)
	v_mfma_f32_16x16x32_bf16 v[110:113], v[138:141], v[180:183], v[110:113]
	v_mfma_f32_16x16x32_bf16 v[106:109], v[148:151], v[180:183], v[106:109]
	s_waitcnt lgkmcnt(3)
	v_mfma_f32_16x16x32_bf16 v[94:97], v[138:141], v[188:191], v[94:97]
	v_mfma_f32_16x16x32_bf16 v[90:93], v[148:151], v[188:191], v[90:93]
	s_waitcnt lgkmcnt(1)
	v_mfma_f32_16x16x32_bf16 v[78:81], v[138:141], v[196:199], v[78:81]
	v_mfma_f32_16x16x32_bf16 v[74:77], v[148:151], v[196:199], v[74:77]
	v_mfma_f32_16x16x32_bf16 v[134:137], v[142:145], v[176:179], v[134:137]
	v_mfma_f32_16x16x32_bf16 v[122:125], v[152:155], v[176:179], v[122:125]
	v_mfma_f32_16x16x32_bf16 v[110:113], v[142:145], v[184:187], v[110:113]
	v_mfma_f32_16x16x32_bf16 v[106:109], v[152:155], v[184:187], v[106:109]
	v_mfma_f32_16x16x32_bf16 v[94:97], v[142:145], v[192:195], v[94:97]
	v_mfma_f32_16x16x32_bf16 v[90:93], v[152:155], v[192:195], v[90:93]
	s_waitcnt lgkmcnt(0)
	v_mfma_f32_16x16x32_bf16 v[78:81], v[142:145], v[200:203], v[78:81]
	v_mfma_f32_16x16x32_bf16 v[74:77], v[152:155], v[200:203], v[74:77]
	v_mfma_f32_16x16x32_bf16 v[118:121], v[156:159], v[172:175], v[118:121]
	v_mfma_f32_16x16x32_bf16 v[114:117], v[164:167], v[172:175], v[114:117]
	v_mfma_f32_16x16x32_bf16 v[102:105], v[156:159], v[180:183], v[102:105]
	v_mfma_f32_16x16x32_bf16 v[98:101], v[164:167], v[180:183], v[98:101]
	v_mfma_f32_16x16x32_bf16 v[86:89], v[156:159], v[188:191], v[86:89]
	v_mfma_f32_16x16x32_bf16 v[82:85], v[164:167], v[188:191], v[82:85]
	v_mfma_f32_16x16x32_bf16 v[70:73], v[156:159], v[196:199], v[70:73]
	v_mfma_f32_16x16x32_bf16 v[66:69], v[164:167], v[196:199], v[66:69]
	v_mfma_f32_16x16x32_bf16 v[118:121], v[160:163], v[176:179], v[118:121]
	v_mfma_f32_16x16x32_bf16 v[114:117], v[168:171], v[176:179], v[114:117]
	v_mfma_f32_16x16x32_bf16 v[102:105], v[160:163], v[184:187], v[102:105]
	v_mfma_f32_16x16x32_bf16 v[98:101], v[168:171], v[184:187], v[98:101]
	v_mfma_f32_16x16x32_bf16 v[86:89], v[160:163], v[192:195], v[86:89]
	v_mfma_f32_16x16x32_bf16 v[82:85], v[168:171], v[192:195], v[82:85]
	v_mfma_f32_16x16x32_bf16 v[70:73], v[160:163], v[200:203], v[70:73]
	v_mfma_f32_16x16x32_bf16 v[66:69], v[168:171], v[200:203], v[66:69]
	s_barrier
	ds_read_b128 v[172:175], v133 offset:16384
	ds_read_b128 v[176:179], v133 offset:17408
	ds_read_b128 v[180:183], v133 offset:18432
	ds_read_b128 v[184:187], v133 offset:19456
	ds_read_b128 v[188:191], v133 offset:20480
	ds_read_b128 v[192:195], v133 offset:21504
	ds_read_b128 v[196:199], v133 offset:22528
	ds_read_b128 v[200:203], v133 offset:23552
	s_mov_b32 m0, s29
	s_nop 0
	buffer_load_dwordx4 v130, s[8:11], s58 offen lds
	s_add_i32 s59, s58, 0xb0000
	s_mov_b32 m0, s34
	s_nop 0
	buffer_load_dwordx4 v131, s[8:11], s58 offen lds
	s_nop 0
	s_mov_b32 m0, s35
	s_nop 0
	buffer_load_dwordx4 v130, s[8:11], s59 offen lds
	s_nop 0
	s_mov_b32 m0, s36
	s_nop 0
	buffer_load_dwordx4 v131, s[8:11], s59 offen lds
	s_nop 0
	s_mov_b32 m0, s28
	s_nop 0
	buffer_load_dwordx4 v130, s[12:15], s60 offen lds
	s_nop 0
	s_mov_b32 m0, s37
	s_nop 0
	buffer_load_dwordx4 v131, s[12:15], s60 offen lds
	s_waitcnt vmcnt(8)
	s_waitcnt lgkmcnt(0)
	s_barrier
	s_waitcnt lgkmcnt(7)
	v_mfma_f32_16x16x32_bf16 v[62:65], v[138:141], v[172:175], v[62:65]
	v_mfma_f32_16x16x32_bf16 v[58:61], v[148:151], v[172:175], v[58:61]
	s_waitcnt lgkmcnt(5)
	v_mfma_f32_16x16x32_bf16 v[46:49], v[138:141], v[180:183], v[46:49]
	v_mfma_f32_16x16x32_bf16 v[42:45], v[148:151], v[180:183], v[42:45]
	s_waitcnt lgkmcnt(3)
	v_mfma_f32_16x16x32_bf16 v[30:33], v[138:141], v[188:191], v[30:33]
	v_mfma_f32_16x16x32_bf16 v[26:29], v[148:151], v[188:191], v[26:29]
	s_waitcnt lgkmcnt(1)
	v_mfma_f32_16x16x32_bf16 v[14:17], v[138:141], v[196:199], v[14:17]
	v_mfma_f32_16x16x32_bf16 v[10:13], v[148:151], v[196:199], v[10:13]
	v_mfma_f32_16x16x32_bf16 v[62:65], v[142:145], v[176:179], v[62:65]
	v_mfma_f32_16x16x32_bf16 v[58:61], v[152:155], v[176:179], v[58:61]
	v_mfma_f32_16x16x32_bf16 v[46:49], v[142:145], v[184:187], v[46:49]
	v_mfma_f32_16x16x32_bf16 v[42:45], v[152:155], v[184:187], v[42:45]
	v_mfma_f32_16x16x32_bf16 v[30:33], v[142:145], v[192:195], v[30:33]
	v_mfma_f32_16x16x32_bf16 v[26:29], v[152:155], v[192:195], v[26:29]
	s_waitcnt lgkmcnt(0)
	v_mfma_f32_16x16x32_bf16 v[14:17], v[142:145], v[200:203], v[14:17]
	v_mfma_f32_16x16x32_bf16 v[10:13], v[152:155], v[200:203], v[10:13]
	v_mfma_f32_16x16x32_bf16 v[54:57], v[156:159], v[172:175], v[54:57]
	v_mfma_f32_16x16x32_bf16 v[50:53], v[164:167], v[172:175], v[50:53]
	v_mfma_f32_16x16x32_bf16 v[38:41], v[156:159], v[180:183], v[38:41]
	v_mfma_f32_16x16x32_bf16 v[34:37], v[164:167], v[180:183], v[34:37]
	v_mfma_f32_16x16x32_bf16 v[22:25], v[156:159], v[188:191], v[22:25]
	v_mfma_f32_16x16x32_bf16 v[18:21], v[164:167], v[188:191], v[18:21]
	v_mfma_f32_16x16x32_bf16 v[6:9], v[156:159], v[196:199], v[6:9]
	v_mfma_f32_16x16x32_bf16 v[2:5], v[164:167], v[196:199], v[2:5]
	v_mfma_f32_16x16x32_bf16 v[54:57], v[160:163], v[176:179], v[54:57]
	v_mfma_f32_16x16x32_bf16 v[50:53], v[168:171], v[176:179], v[50:53]
	v_mfma_f32_16x16x32_bf16 v[38:41], v[160:163], v[184:187], v[38:41]
	v_mfma_f32_16x16x32_bf16 v[34:37], v[168:171], v[184:187], v[34:37]
	v_mfma_f32_16x16x32_bf16 v[22:25], v[160:163], v[192:195], v[22:25]
	v_mfma_f32_16x16x32_bf16 v[18:21], v[168:171], v[192:195], v[18:21]
	v_mfma_f32_16x16x32_bf16 v[6:9], v[160:163], v[200:203], v[6:9]
	v_mfma_f32_16x16x32_bf16 v[2:5], v[168:171], v[200:203], v[2:5]
	s_barrier
	v_add_u32_e32 v147, 0x18000, v132
	ds_read_b128 v[138:141], v147
	ds_read_b128 v[142:145], v147 offset:1024
	ds_read_b128 v[148:151], v147 offset:2048
	ds_read_b128 v[152:155], v147 offset:3072
	v_add_u32_e32 v147, 0x1c000, v132
	ds_read_b128 v[156:159], v147
	ds_read_b128 v[160:163], v147 offset:1024
	ds_read_b128 v[164:167], v147 offset:2048
	ds_read_b128 v[168:171], v147 offset:3072
	ds_read_b128 v[172:175], v133 offset:32768
	ds_read_b128 v[176:179], v133 offset:33792
	ds_read_b128 v[180:183], v133 offset:34816
	ds_read_b128 v[184:187], v133 offset:35840
	ds_read_b128 v[188:191], v133 offset:36864
	ds_read_b128 v[192:195], v133 offset:37888
	ds_read_b128 v[196:199], v133 offset:38912
	ds_read_b128 v[200:203], v133 offset:39936
	s_add_i32 s59, s60, 0xb0000
	s_mov_b32 m0, s38
	s_nop 0
	buffer_load_dwordx4 v130, s[12:15], s59 offen lds
	s_nop 0
	s_mov_b32 m0, s39
	s_nop 0
	buffer_load_dwordx4 v131, s[12:15], s59 offen lds
	s_waitcnt vmcnt(8)
	s_waitcnt lgkmcnt(0)
	s_barrier
	s_waitcnt lgkmcnt(7)
	v_mfma_f32_16x16x32_bf16 v[134:137], v[138:141], v[172:175], v[134:137]
	v_mfma_f32_16x16x32_bf16 v[122:125], v[148:151], v[172:175], v[122:125]
	s_waitcnt lgkmcnt(5)
	v_mfma_f32_16x16x32_bf16 v[110:113], v[138:141], v[180:183], v[110:113]
	v_mfma_f32_16x16x32_bf16 v[106:109], v[148:151], v[180:183], v[106:109]
	s_waitcnt lgkmcnt(3)
	v_mfma_f32_16x16x32_bf16 v[94:97], v[138:141], v[188:191], v[94:97]
	v_mfma_f32_16x16x32_bf16 v[90:93], v[148:151], v[188:191], v[90:93]
	s_waitcnt lgkmcnt(1)
	v_mfma_f32_16x16x32_bf16 v[78:81], v[138:141], v[196:199], v[78:81]
	v_mfma_f32_16x16x32_bf16 v[74:77], v[148:151], v[196:199], v[74:77]
	v_mfma_f32_16x16x32_bf16 v[134:137], v[142:145], v[176:179], v[134:137]
	v_mfma_f32_16x16x32_bf16 v[122:125], v[152:155], v[176:179], v[122:125]
	v_mfma_f32_16x16x32_bf16 v[110:113], v[142:145], v[184:187], v[110:113]
	v_mfma_f32_16x16x32_bf16 v[106:109], v[152:155], v[184:187], v[106:109]
	v_mfma_f32_16x16x32_bf16 v[94:97], v[142:145], v[192:195], v[94:97]
	v_mfma_f32_16x16x32_bf16 v[90:93], v[152:155], v[192:195], v[90:93]
	s_waitcnt lgkmcnt(0)
	v_mfma_f32_16x16x32_bf16 v[78:81], v[142:145], v[200:203], v[78:81]
	v_mfma_f32_16x16x32_bf16 v[74:77], v[152:155], v[200:203], v[74:77]
	v_mfma_f32_16x16x32_bf16 v[118:121], v[156:159], v[172:175], v[118:121]
	v_mfma_f32_16x16x32_bf16 v[114:117], v[164:167], v[172:175], v[114:117]
	v_mfma_f32_16x16x32_bf16 v[102:105], v[156:159], v[180:183], v[102:105]
	v_mfma_f32_16x16x32_bf16 v[98:101], v[164:167], v[180:183], v[98:101]
	v_mfma_f32_16x16x32_bf16 v[86:89], v[156:159], v[188:191], v[86:89]
	v_mfma_f32_16x16x32_bf16 v[82:85], v[164:167], v[188:191], v[82:85]
	v_mfma_f32_16x16x32_bf16 v[70:73], v[156:159], v[196:199], v[70:73]
	v_mfma_f32_16x16x32_bf16 v[66:69], v[164:167], v[196:199], v[66:69]
	v_mfma_f32_16x16x32_bf16 v[118:121], v[160:163], v[176:179], v[118:121]
	v_mfma_f32_16x16x32_bf16 v[114:117], v[168:171], v[176:179], v[114:117]
	v_mfma_f32_16x16x32_bf16 v[102:105], v[160:163], v[184:187], v[102:105]
	v_mfma_f32_16x16x32_bf16 v[98:101], v[168:171], v[184:187], v[98:101]
	v_mfma_f32_16x16x32_bf16 v[86:89], v[160:163], v[192:195], v[86:89]
	v_mfma_f32_16x16x32_bf16 v[82:85], v[168:171], v[192:195], v[82:85]
	v_mfma_f32_16x16x32_bf16 v[70:73], v[160:163], v[200:203], v[70:73]
	v_mfma_f32_16x16x32_bf16 v[66:69], v[168:171], v[200:203], v[66:69]
	s_barrier
	ds_read_b128 v[172:175], v133 offset:49152
	ds_read_b128 v[176:179], v133 offset:50176
	ds_read_b128 v[180:183], v133 offset:51200
	ds_read_b128 v[184:187], v133 offset:52224
	ds_read_b128 v[188:191], v133 offset:53248
	ds_read_b128 v[192:195], v133 offset:54272
	ds_read_b128 v[196:199], v133 offset:55296
	ds_read_b128 v[200:203], v133 offset:56320
	s_add_i32 s59, s58, 0x80
	s_mov_b32 m0, s40
	s_nop 0
	buffer_load_dwordx4 v130, s[8:11], s59 offen lds
	s_add_i32 s58, s58, 0xb0080
	s_mov_b32 m0, s41
	s_nop 0
	buffer_load_dwordx4 v131, s[8:11], s59 offen lds
	s_nop 0
	s_mov_b32 m0, s44
	s_nop 0
	buffer_load_dwordx4 v130, s[8:11], s58 offen lds
	s_nop 0
	s_mov_b32 m0, s45
	s_nop 0
	buffer_load_dwordx4 v131, s[8:11], s58 offen lds
	s_nop 0
	s_mov_b32 m0, s42
	s_nop 0
	buffer_load_dwordx4 v130, s[12:15], s55 offen lds
	s_nop 0
	s_mov_b32 m0, s43
	s_nop 0
	buffer_load_dwordx4 v131, s[12:15], s55 offen lds
	s_waitcnt vmcnt(8)
	s_waitcnt lgkmcnt(0)
	s_barrier
	s_waitcnt lgkmcnt(7)
	v_mfma_f32_16x16x32_bf16 v[62:65], v[138:141], v[172:175], v[62:65]
	v_mfma_f32_16x16x32_bf16 v[58:61], v[148:151], v[172:175], v[58:61]
	s_waitcnt lgkmcnt(5)
	v_mfma_f32_16x16x32_bf16 v[46:49], v[138:141], v[180:183], v[46:49]
	v_mfma_f32_16x16x32_bf16 v[42:45], v[148:151], v[180:183], v[42:45]
	s_waitcnt lgkmcnt(3)
	v_mfma_f32_16x16x32_bf16 v[30:33], v[138:141], v[188:191], v[30:33]
	v_mfma_f32_16x16x32_bf16 v[26:29], v[148:151], v[188:191], v[26:29]
	s_waitcnt lgkmcnt(1)
	v_mfma_f32_16x16x32_bf16 v[14:17], v[138:141], v[196:199], v[14:17]
	v_mfma_f32_16x16x32_bf16 v[10:13], v[148:151], v[196:199], v[10:13]
	v_mfma_f32_16x16x32_bf16 v[62:65], v[142:145], v[176:179], v[62:65]
	v_mfma_f32_16x16x32_bf16 v[58:61], v[152:155], v[176:179], v[58:61]
	v_mfma_f32_16x16x32_bf16 v[46:49], v[142:145], v[184:187], v[46:49]
	v_mfma_f32_16x16x32_bf16 v[42:45], v[152:155], v[184:187], v[42:45]
	v_mfma_f32_16x16x32_bf16 v[30:33], v[142:145], v[192:195], v[30:33]
	v_mfma_f32_16x16x32_bf16 v[26:29], v[152:155], v[192:195], v[26:29]
	s_waitcnt lgkmcnt(0)
	v_mfma_f32_16x16x32_bf16 v[14:17], v[142:145], v[200:203], v[14:17]
	v_mfma_f32_16x16x32_bf16 v[10:13], v[152:155], v[200:203], v[10:13]
	v_mfma_f32_16x16x32_bf16 v[54:57], v[156:159], v[172:175], v[54:57]
	v_mfma_f32_16x16x32_bf16 v[50:53], v[164:167], v[172:175], v[50:53]
	v_mfma_f32_16x16x32_bf16 v[38:41], v[156:159], v[180:183], v[38:41]
	v_mfma_f32_16x16x32_bf16 v[34:37], v[164:167], v[180:183], v[34:37]
	v_mfma_f32_16x16x32_bf16 v[22:25], v[156:159], v[188:191], v[22:25]
	v_mfma_f32_16x16x32_bf16 v[18:21], v[164:167], v[188:191], v[18:21]
	v_mfma_f32_16x16x32_bf16 v[6:9], v[156:159], v[196:199], v[6:9]
	v_mfma_f32_16x16x32_bf16 v[2:5], v[164:167], v[196:199], v[2:5]
	v_mfma_f32_16x16x32_bf16 v[54:57], v[160:163], v[176:179], v[54:57]
	v_mfma_f32_16x16x32_bf16 v[50:53], v[168:171], v[176:179], v[50:53]
	v_mfma_f32_16x16x32_bf16 v[38:41], v[160:163], v[184:187], v[38:41]
	v_mfma_f32_16x16x32_bf16 v[34:37], v[168:171], v[184:187], v[34:37]
	v_mfma_f32_16x16x32_bf16 v[22:25], v[160:163], v[192:195], v[22:25]
	v_mfma_f32_16x16x32_bf16 v[18:21], v[168:171], v[192:195], v[18:21]
	v_mfma_f32_16x16x32_bf16 v[6:9], v[160:163], v[200:203], v[6:9]
	v_mfma_f32_16x16x32_bf16 v[2:5], v[168:171], v[200:203], v[2:5]
	s_barrier
	s_add_i32 s0, s0, 2
	s_addk_i32 s1, 0x100
	s_cmp_gt_u32 s0, 41
	s_cbranch_scc0 .LBB0_467
	s_andn2_b64 vcc, exec, s[6:7]
	s_cbranch_vccnz .LBB0_455
	v_mov_b32_e32 v2, 0
	s_mov_b32 s18, s50
	s_mov_b32 s31, s51
	s_mov_b32 s33, s54
	s_mov_b32 s3, s53
	s_mov_b32 s49, s52
	v_mov_b32_e32 v3, v2
	v_mov_b32_e32 v4, v2
	v_mov_b32_e32 v5, v2
	v_mov_b32_e32 v6, v2
	v_mov_b32_e32 v7, v2
	v_mov_b32_e32 v8, v2
	v_mov_b32_e32 v9, v2
	v_mov_b32_e32 v18, v2
	v_mov_b32_e32 v19, v2
	v_mov_b32_e32 v20, v2
	v_mov_b32_e32 v21, v2
	v_mov_b32_e32 v22, v2
	v_mov_b32_e32 v23, v2
	v_mov_b32_e32 v24, v2
	v_mov_b32_e32 v25, v2
	v_mov_b32_e32 v34, v2
	v_mov_b32_e32 v35, v2
	v_mov_b32_e32 v36, v2
	v_mov_b32_e32 v37, v2
	v_mov_b32_e32 v38, v2
	v_mov_b32_e32 v39, v2
	v_mov_b32_e32 v40, v2
	v_mov_b32_e32 v41, v2
	v_mov_b32_e32 v50, v2
	v_mov_b32_e32 v51, v2
	v_mov_b32_e32 v52, v2
	v_mov_b32_e32 v53, v2
	v_mov_b32_e32 v54, v2
	v_mov_b32_e32 v55, v2
	v_mov_b32_e32 v56, v2
	v_mov_b32_e32 v57, v2
	v_mov_b32_e32 v10, v2
	v_mov_b32_e32 v11, v2
	v_mov_b32_e32 v12, v2
	v_mov_b32_e32 v13, v2
	v_mov_b32_e32 v14, v2
	v_mov_b32_e32 v15, v2
	v_mov_b32_e32 v16, v2
	v_mov_b32_e32 v17, v2
	v_mov_b32_e32 v26, v2
	v_mov_b32_e32 v27, v2
	v_mov_b32_e32 v28, v2
	v_mov_b32_e32 v29, v2
	v_mov_b32_e32 v30, v2
	v_mov_b32_e32 v31, v2
	v_mov_b32_e32 v32, v2
	v_mov_b32_e32 v33, v2
	v_mov_b32_e32 v42, v2
	v_mov_b32_e32 v43, v2
	v_mov_b32_e32 v44, v2
	v_mov_b32_e32 v45, v2
	v_mov_b32_e32 v46, v2
	v_mov_b32_e32 v47, v2
	v_mov_b32_e32 v48, v2
	v_mov_b32_e32 v49, v2
	v_mov_b32_e32 v58, v2
	v_mov_b32_e32 v59, v2
	v_mov_b32_e32 v60, v2
	v_mov_b32_e32 v61, v2
	v_mov_b32_e32 v62, v2
	v_mov_b32_e32 v63, v2
	v_mov_b32_e32 v64, v2
	v_mov_b32_e32 v65, v2
	v_mov_b32_e32 v66, v2
	v_mov_b32_e32 v67, v2
	v_mov_b32_e32 v68, v2
	v_mov_b32_e32 v69, v2
	v_mov_b32_e32 v70, v2
	v_mov_b32_e32 v71, v2
	v_mov_b32_e32 v72, v2
	v_mov_b32_e32 v73, v2
	v_mov_b32_e32 v82, v2
	v_mov_b32_e32 v83, v2
	v_mov_b32_e32 v84, v2
	v_mov_b32_e32 v85, v2
	v_mov_b32_e32 v86, v2
	v_mov_b32_e32 v87, v2
	v_mov_b32_e32 v88, v2
	v_mov_b32_e32 v89, v2
	v_mov_b32_e32 v98, v2
	v_mov_b32_e32 v99, v2
	v_mov_b32_e32 v100, v2
	v_mov_b32_e32 v101, v2
	v_mov_b32_e32 v102, v2
	v_mov_b32_e32 v103, v2
	v_mov_b32_e32 v104, v2
	v_mov_b32_e32 v105, v2
	v_mov_b32_e32 v114, v2
	v_mov_b32_e32 v115, v2
	v_mov_b32_e32 v116, v2
	v_mov_b32_e32 v117, v2
	v_mov_b32_e32 v118, v2
	v_mov_b32_e32 v119, v2
	v_mov_b32_e32 v120, v2
	v_mov_b32_e32 v121, v2
	v_mov_b32_e32 v74, v2
	v_mov_b32_e32 v75, v2
	v_mov_b32_e32 v76, v2
	v_mov_b32_e32 v77, v2
	v_mov_b32_e32 v78, v2
	v_mov_b32_e32 v79, v2
	v_mov_b32_e32 v80, v2
	v_mov_b32_e32 v81, v2
	v_mov_b32_e32 v90, v2
	v_mov_b32_e32 v91, v2
	v_mov_b32_e32 v92, v2
	v_mov_b32_e32 v93, v2
	v_mov_b32_e32 v94, v2
	v_mov_b32_e32 v95, v2
	v_mov_b32_e32 v96, v2
	v_mov_b32_e32 v97, v2
	v_mov_b32_e32 v106, v2
	v_mov_b32_e32 v107, v2
	v_mov_b32_e32 v108, v2
	v_mov_b32_e32 v109, v2
	v_mov_b32_e32 v110, v2
	v_mov_b32_e32 v111, v2
	v_mov_b32_e32 v112, v2
	v_mov_b32_e32 v113, v2
	v_mov_b32_e32 v122, v2
	v_mov_b32_e32 v123, v2
	v_mov_b32_e32 v124, v2
	v_mov_b32_e32 v125, v2
	v_mov_b32_e32 v134, v2
	v_mov_b32_e32 v135, v2
	v_mov_b32_e32 v136, v2
	v_mov_b32_e32 v137, v2
	s_branch .LBB0_455

.LBB0_619:
	ds_read_b128 v[38:41], v210
	ds_read_b128 v[42:45], v210 offset:1024
	ds_read_b128 v[46:49], v210 offset:2048
	ds_read_b128 v[58:61], v210 offset:3072
	ds_read_b128 v[142:145], v211
	ds_read_b128 v[146:149], v211 offset:1024
	ds_read_b128 v[150:153], v211 offset:2048
	ds_read_b128 v[154:157], v211 offset:3072
	s_add_i32 s6, s1, 0xfffe0080
	s_cmp_eq_u32 s3, 4
	s_cselect_b32 s8, s75, s6
	s_cselect_b32 s7, s0, s2
	s_add_i32 s6, s8, 0x80
	ds_read_b128 v[166:169], v212
	ds_read_b128 v[170:173], v212 offset:1024
	ds_read_b128 v[174:177], v212 offset:2048
	ds_read_b128 v[178:181], v212 offset:3072
	ds_read_b128 v[190:193], v212 offset:4096
	ds_read_b128 v[194:197], v212 offset:5120
	ds_read_b128 v[198:201], v212 offset:6144
	ds_read_b128 v[216:219], v212 offset:7168
	s_mov_b32 m0, s68
	s_nop 0
	buffer_load_dwordx4 v206, s[16:19], s1 offen lds
	s_nop 0
	s_mov_b32 m0, s69
	s_nop 0
	buffer_load_dwordx4 v207, s[16:19], s1 offen lds
	s_waitcnt vmcnt(8)
	s_waitcnt lgkmcnt(0)
	s_barrier
	s_waitcnt lgkmcnt(7)
	v_mfma_i32_16x16x64_i8 v[162:165], v[38:41], v[166:169], v[162:165]
	v_mfma_i32_16x16x64_i8 v[158:161], v[46:49], v[166:169], v[158:161]
	s_waitcnt lgkmcnt(5)
	v_mfma_i32_16x16x64_i8 v[130:133], v[38:41], v[174:177], v[130:133]
	v_mfma_i32_16x16x64_i8 v[126:129], v[46:49], v[174:177], v[126:129]
	s_waitcnt lgkmcnt(3)
	v_mfma_i32_16x16x64_i8 v[114:117], v[38:41], v[190:193], v[114:117]
	v_mfma_i32_16x16x64_i8 v[110:113], v[46:49], v[190:193], v[110:113]
	s_waitcnt lgkmcnt(1)
	v_mfma_i32_16x16x64_i8 v[98:101], v[38:41], v[198:201], v[98:101]
	v_mfma_i32_16x16x64_i8 v[94:97], v[46:49], v[198:201], v[94:97]
	v_mfma_i32_16x16x64_i8 v[162:165], v[42:45], v[170:173], v[162:165]
	v_mfma_i32_16x16x64_i8 v[158:161], v[58:61], v[170:173], v[158:161]
	v_mfma_i32_16x16x64_i8 v[130:133], v[42:45], v[178:181], v[130:133]
	v_mfma_i32_16x16x64_i8 v[126:129], v[58:61], v[178:181], v[126:129]
	v_mfma_i32_16x16x64_i8 v[114:117], v[42:45], v[194:197], v[114:117]
	v_mfma_i32_16x16x64_i8 v[110:113], v[58:61], v[194:197], v[110:113]
	s_waitcnt lgkmcnt(0)
	v_mfma_i32_16x16x64_i8 v[98:101], v[42:45], v[216:219], v[98:101]
	v_mfma_i32_16x16x64_i8 v[94:97], v[58:61], v[216:219], v[94:97]
	v_mfma_i32_16x16x64_i8 v[138:141], v[142:145], v[166:169], v[138:141]
	v_mfma_i32_16x16x64_i8 v[134:137], v[150:153], v[166:169], v[134:137]
	v_mfma_i32_16x16x64_i8 v[122:125], v[142:145], v[174:177], v[122:125]
	v_mfma_i32_16x16x64_i8 v[118:121], v[150:153], v[174:177], v[118:121]
	v_mfma_i32_16x16x64_i8 v[106:109], v[142:145], v[190:193], v[106:109]
	v_mfma_i32_16x16x64_i8 v[102:105], v[150:153], v[190:193], v[102:105]
	v_mfma_i32_16x16x64_i8 v[90:93], v[142:145], v[198:201], v[90:93]
	v_mfma_i32_16x16x64_i8 v[86:89], v[150:153], v[198:201], v[86:89]
	v_mfma_i32_16x16x64_i8 v[138:141], v[146:149], v[170:173], v[138:141]
	v_mfma_i32_16x16x64_i8 v[134:137], v[154:157], v[170:173], v[134:137]
	v_mfma_i32_16x16x64_i8 v[122:125], v[146:149], v[178:181], v[122:125]
	v_mfma_i32_16x16x64_i8 v[118:121], v[154:157], v[178:181], v[118:121]
	v_mfma_i32_16x16x64_i8 v[106:109], v[146:149], v[194:197], v[106:109]
	v_mfma_i32_16x16x64_i8 v[102:105], v[154:157], v[194:197], v[102:105]
	v_mfma_i32_16x16x64_i8 v[90:93], v[146:149], v[216:219], v[90:93]
	v_mfma_i32_16x16x64_i8 v[86:89], v[154:157], v[216:219], v[86:89]
	s_barrier
	ds_read_b128 v[166:169], v212 offset:16384
	ds_read_b128 v[170:173], v212 offset:17408
	ds_read_b128 v[174:177], v212 offset:18432
	ds_read_b128 v[178:181], v212 offset:19456
	ds_read_b128 v[190:193], v212 offset:20480
	ds_read_b128 v[194:197], v212 offset:21504
	ds_read_b128 v[198:201], v212 offset:22528
	ds_read_b128 v[216:219], v212 offset:23552
	s_mov_b32 m0, s48
	s_nop 0
	buffer_load_dwordx4 v204, s[12:15], s7 offen lds
	s_add_i32 s9, s7, 0x20000
	s_mov_b32 m0, s49
	s_nop 0
	buffer_load_dwordx4 v205, s[12:15], s7 offen lds
	s_nop 0
	s_mov_b32 m0, s50
	s_nop 0
	buffer_load_dwordx4 v204, s[12:15], s9 offen lds
	s_nop 0
	s_mov_b32 m0, s51
	s_nop 0
	buffer_load_dwordx4 v205, s[12:15], s9 offen lds
	s_nop 0
	s_mov_b32 m0, s47
	s_nop 0
	buffer_load_dwordx4 v206, s[16:19], s8 offen lds
	s_nop 0
	s_mov_b32 m0, s52
	s_nop 0
	buffer_load_dwordx4 v207, s[16:19], s8 offen lds
	s_waitcnt vmcnt(8)
	s_waitcnt lgkmcnt(0)
	s_barrier
	s_waitcnt lgkmcnt(7)
	v_mfma_i32_16x16x64_i8 v[82:85], v[38:41], v[166:169], v[82:85]
	v_mfma_i32_16x16x64_i8 v[78:81], v[46:49], v[166:169], v[78:81]
	s_waitcnt lgkmcnt(5)
	v_mfma_i32_16x16x64_i8 v[66:69], v[38:41], v[174:177], v[66:69]
	v_mfma_i32_16x16x64_i8 v[62:65], v[46:49], v[174:177], v[62:65]
	s_waitcnt lgkmcnt(3)
	v_mfma_i32_16x16x64_i8 v[34:37], v[38:41], v[190:193], v[34:37]
	v_mfma_i32_16x16x64_i8 v[30:33], v[46:49], v[190:193], v[30:33]
	s_waitcnt lgkmcnt(1)
	v_mfma_i32_16x16x64_i8 v[18:21], v[38:41], v[198:201], v[18:21]
	v_mfma_i32_16x16x64_i8 v[14:17], v[46:49], v[198:201], v[14:17]
	v_mfma_i32_16x16x64_i8 v[82:85], v[42:45], v[170:173], v[82:85]
	v_mfma_i32_16x16x64_i8 v[78:81], v[58:61], v[170:173], v[78:81]
	v_mfma_i32_16x16x64_i8 v[66:69], v[42:45], v[178:181], v[66:69]
	v_mfma_i32_16x16x64_i8 v[62:65], v[58:61], v[178:181], v[62:65]
	v_mfma_i32_16x16x64_i8 v[34:37], v[42:45], v[194:197], v[34:37]
	v_mfma_i32_16x16x64_i8 v[30:33], v[58:61], v[194:197], v[30:33]
	s_waitcnt lgkmcnt(0)
	v_mfma_i32_16x16x64_i8 v[18:21], v[42:45], v[216:219], v[18:21]
	v_mfma_i32_16x16x64_i8 v[14:17], v[58:61], v[216:219], v[14:17]
	v_mfma_i32_16x16x64_i8 v[50:53], v[150:153], v[174:177], v[50:53]
	v_mfma_i32_16x16x64_i8 v[26:29], v[142:145], v[190:193], v[26:29]
	v_mfma_i32_16x16x64_i8 v[22:25], v[150:153], v[190:193], v[22:25]
	v_mfma_i32_16x16x64_i8 v[10:13], v[142:145], v[198:201], v[10:13]
	v_mfma_i32_16x16x64_i8 v[4:7], v[150:153], v[198:201], v[6:9]
	v_mfma_i32_16x16x64_i8 v[38:41], v[142:145], v[166:169], v[74:77]
	v_mfma_i32_16x16x64_i8 v[42:45], v[150:153], v[166:169], v[70:73]
	v_mfma_i32_16x16x64_i8 v[46:49], v[142:145], v[174:177], v[54:57]
	v_mfma_i32_16x16x64_i8 v[50:53], v[154:157], v[178:181], v[50:53]
	v_mfma_i32_16x16x64_i8 v[26:29], v[146:149], v[194:197], v[26:29]
	v_mfma_i32_16x16x64_i8 v[22:25], v[154:157], v[194:197], v[22:25]
	v_mfma_i32_16x16x64_i8 v[10:13], v[146:149], v[216:219], v[10:13]
	v_mfma_i32_16x16x64_i8 v[4:7], v[154:157], v[216:219], v[4:7]
	v_mfma_i32_16x16x64_i8 v[38:41], v[146:149], v[170:173], v[38:41]
	v_mfma_i32_16x16x64_i8 v[42:45], v[154:157], v[170:173], v[42:45]
	v_mfma_i32_16x16x64_i8 v[46:49], v[146:149], v[178:181], v[46:49]
	s_barrier
	ds_read_b128 v[54:57], v213
	ds_read_b128 v[58:61], v213 offset:1024
	ds_read_b128 v[70:73], v213 offset:2048
	ds_read_b128 v[74:77], v213 offset:3072
	ds_read_b128 v[142:145], v214
	ds_read_b128 v[146:149], v214 offset:1024
	ds_read_b128 v[150:153], v214 offset:2048
	ds_read_b128 v[154:157], v214 offset:3072
	ds_read_b128 v[166:169], v212 offset:32768
	ds_read_b128 v[170:173], v212 offset:33792
	ds_read_b128 v[174:177], v212 offset:34816
	ds_read_b128 v[178:181], v212 offset:35840
	ds_read_b128 v[190:193], v212 offset:36864
	ds_read_b128 v[194:197], v212 offset:37888
	ds_read_b128 v[198:201], v212 offset:38912
	ds_read_b128 v[216:219], v212 offset:39936
	s_add_i32 s8, s8, 0x20000
	s_mov_b32 m0, s53
	s_nop 0
	buffer_load_dwordx4 v206, s[16:19], s8 offen lds
	s_nop 0
	s_mov_b32 m0, s54
	s_nop 0
	buffer_load_dwordx4 v207, s[16:19], s8 offen lds
	s_waitcnt vmcnt(8)
	s_waitcnt lgkmcnt(0)
	s_barrier
	s_waitcnt lgkmcnt(7)
	v_mfma_i32_16x16x64_i8 v[162:165], v[54:57], v[166:169], v[162:165]
	v_mfma_i32_16x16x64_i8 v[158:161], v[70:73], v[166:169], v[158:161]
	s_waitcnt lgkmcnt(5)
	v_mfma_i32_16x16x64_i8 v[130:133], v[54:57], v[174:177], v[130:133]
	v_mfma_i32_16x16x64_i8 v[126:129], v[70:73], v[174:177], v[126:129]
	s_waitcnt lgkmcnt(3)
	v_mfma_i32_16x16x64_i8 v[114:117], v[54:57], v[190:193], v[114:117]
	v_mfma_i32_16x16x64_i8 v[110:113], v[70:73], v[190:193], v[110:113]
	s_waitcnt lgkmcnt(1)
	v_mfma_i32_16x16x64_i8 v[98:101], v[54:57], v[198:201], v[98:101]
	v_mfma_i32_16x16x64_i8 v[94:97], v[70:73], v[198:201], v[94:97]
	v_mfma_i32_16x16x64_i8 v[162:165], v[58:61], v[170:173], v[162:165]
	v_mfma_i32_16x16x64_i8 v[158:161], v[74:77], v[170:173], v[158:161]
	v_mfma_i32_16x16x64_i8 v[130:133], v[58:61], v[178:181], v[130:133]
	v_mfma_i32_16x16x64_i8 v[126:129], v[74:77], v[178:181], v[126:129]
	v_mfma_i32_16x16x64_i8 v[114:117], v[58:61], v[194:197], v[114:117]
	v_mfma_i32_16x16x64_i8 v[110:113], v[74:77], v[194:197], v[110:113]
	s_waitcnt lgkmcnt(0)
	v_mfma_i32_16x16x64_i8 v[98:101], v[58:61], v[216:219], v[98:101]
	v_mfma_i32_16x16x64_i8 v[94:97], v[74:77], v[216:219], v[94:97]
	v_mfma_i32_16x16x64_i8 v[138:141], v[142:145], v[166:169], v[138:141]
	v_mfma_i32_16x16x64_i8 v[134:137], v[150:153], v[166:169], v[134:137]
	v_mfma_i32_16x16x64_i8 v[122:125], v[142:145], v[174:177], v[122:125]
	v_mfma_i32_16x16x64_i8 v[118:121], v[150:153], v[174:177], v[118:121]
	v_mfma_i32_16x16x64_i8 v[106:109], v[142:145], v[190:193], v[106:109]
	v_mfma_i32_16x16x64_i8 v[102:105], v[150:153], v[190:193], v[102:105]
	v_mfma_i32_16x16x64_i8 v[90:93], v[142:145], v[198:201], v[90:93]
	v_mfma_i32_16x16x64_i8 v[86:89], v[150:153], v[198:201], v[86:89]
	v_mfma_i32_16x16x64_i8 v[138:141], v[146:149], v[170:173], v[138:141]
	v_mfma_i32_16x16x64_i8 v[134:137], v[154:157], v[170:173], v[134:137]
	v_mfma_i32_16x16x64_i8 v[122:125], v[146:149], v[178:181], v[122:125]
	v_mfma_i32_16x16x64_i8 v[118:121], v[154:157], v[178:181], v[118:121]
	v_mfma_i32_16x16x64_i8 v[106:109], v[146:149], v[194:197], v[106:109]
	v_mfma_i32_16x16x64_i8 v[102:105], v[154:157], v[194:197], v[102:105]
	v_mfma_i32_16x16x64_i8 v[90:93], v[146:149], v[216:219], v[90:93]
	v_mfma_i32_16x16x64_i8 v[86:89], v[154:157], v[216:219], v[86:89]
	s_barrier
	ds_read_b128 v[166:169], v212 offset:49152
	ds_read_b128 v[170:173], v212 offset:50176
	ds_read_b128 v[174:177], v212 offset:51200
	ds_read_b128 v[178:181], v212 offset:52224
	ds_read_b128 v[190:193], v212 offset:53248
	ds_read_b128 v[194:197], v212 offset:54272
	ds_read_b128 v[198:201], v212 offset:55296
	ds_read_b128 v[216:219], v212 offset:56320
	s_or_b32 s8, s7, 0x80
	s_mov_b32 m0, s62
	s_nop 0
	buffer_load_dwordx4 v204, s[12:15], s8 offen lds
	s_add_i32 s7, s7, 0x20080
	s_mov_b32 m0, s63
	s_nop 0
	buffer_load_dwordx4 v205, s[12:15], s8 offen lds
	s_nop 0
	s_mov_b32 m0, s66
	s_nop 0
	buffer_load_dwordx4 v204, s[12:15], s7 offen lds
	s_nop 0
	s_mov_b32 m0, s67
	s_nop 0
	buffer_load_dwordx4 v205, s[12:15], s7 offen lds
	s_nop 0
	s_mov_b32 m0, s64
	s_nop 0
	buffer_load_dwordx4 v206, s[16:19], s6 offen lds
	s_nop 0
	s_mov_b32 m0, s65
	s_nop 0
	buffer_load_dwordx4 v207, s[16:19], s6 offen lds
	s_waitcnt vmcnt(8)
	s_waitcnt lgkmcnt(0)
	s_barrier
	s_waitcnt lgkmcnt(7)
	v_mfma_i32_16x16x64_i8 v[82:85], v[54:57], v[166:169], v[82:85]
	v_mfma_i32_16x16x64_i8 v[78:81], v[70:73], v[166:169], v[78:81]
	s_waitcnt lgkmcnt(5)
	v_mfma_i32_16x16x64_i8 v[66:69], v[54:57], v[174:177], v[66:69]
	v_mfma_i32_16x16x64_i8 v[62:65], v[70:73], v[174:177], v[62:65]
	s_waitcnt lgkmcnt(3)
	v_mfma_i32_16x16x64_i8 v[34:37], v[54:57], v[190:193], v[34:37]
	v_mfma_i32_16x16x64_i8 v[30:33], v[70:73], v[190:193], v[30:33]
	s_waitcnt lgkmcnt(1)
	v_mfma_i32_16x16x64_i8 v[18:21], v[54:57], v[198:201], v[18:21]
	v_mfma_i32_16x16x64_i8 v[14:17], v[70:73], v[198:201], v[14:17]
	v_mfma_i32_16x16x64_i8 v[82:85], v[58:61], v[170:173], v[82:85]
	v_mfma_i32_16x16x64_i8 v[78:81], v[74:77], v[170:173], v[78:81]
	v_mfma_i32_16x16x64_i8 v[66:69], v[58:61], v[178:181], v[66:69]
	v_mfma_i32_16x16x64_i8 v[62:65], v[74:77], v[178:181], v[62:65]
	v_mfma_i32_16x16x64_i8 v[34:37], v[58:61], v[194:197], v[34:37]
	v_mfma_i32_16x16x64_i8 v[30:33], v[74:77], v[194:197], v[30:33]
	s_waitcnt lgkmcnt(0)
	v_mfma_i32_16x16x64_i8 v[18:21], v[58:61], v[216:219], v[18:21]
	v_mfma_i32_16x16x64_i8 v[14:17], v[74:77], v[216:219], v[14:17]
	v_mfma_i32_16x16x64_i8 v[38:41], v[142:145], v[166:169], v[38:41]
	v_mfma_i32_16x16x64_i8 v[74:77], v[146:149], v[170:173], v[38:41]
	v_mfma_i32_16x16x64_i8 v[38:41], v[150:153], v[166:169], v[42:45]
	v_mfma_i32_16x16x64_i8 v[70:73], v[154:157], v[170:173], v[38:41]
	v_mfma_i32_16x16x64_i8 v[38:41], v[142:145], v[174:177], v[46:49]
	v_mfma_i32_16x16x64_i8 v[54:57], v[146:149], v[178:181], v[38:41]
	v_mfma_i32_16x16x64_i8 v[38:41], v[150:153], v[174:177], v[50:53]
	v_mfma_i32_16x16x64_i8 v[26:29], v[142:145], v[190:193], v[26:29]
	v_mfma_i32_16x16x64_i8 v[22:25], v[150:153], v[190:193], v[22:25]
	v_mfma_i32_16x16x64_i8 v[8:11], v[142:145], v[198:201], v[10:13]
	v_mfma_i32_16x16x64_i8 v[4:7], v[150:153], v[198:201], v[4:7]
	v_mfma_i32_16x16x64_i8 v[50:53], v[154:157], v[178:181], v[38:41]
	v_mfma_i32_16x16x64_i8 v[26:29], v[146:149], v[194:197], v[26:29]
	v_mfma_i32_16x16x64_i8 v[22:25], v[154:157], v[194:197], v[22:25]
	v_mfma_i32_16x16x64_i8 v[10:13], v[146:149], v[216:219], v[8:11]
	v_mfma_i32_16x16x64_i8 v[6:9], v[154:157], v[216:219], v[4:7]
	s_barrier
	s_add_i32 s3, s3, 2
	s_addk_i32 s1, 0x100
	s_addk_i32 s2, 0x100
	s_cmp_gt_u32 s3, 5
	s_cbranch_scc0 .LBB0_619
	s_and_b64 vcc, exec, s[34:35]
	s_cbranch_vccz .LBB0_622
	s_barrier

.LBB0_943:
	v_add_u32_e32 v150, 0x10000, v8
	v_add_u32_e32 v166, 0x14000, v8
	ds_read_b128 v[10:13], v150
	ds_read_b128 v[14:17], v150 offset:1024
	ds_read_b128 v[146:149], v150 offset:2048
	ds_read_b128 v[150:153], v150 offset:3072
	ds_read_b128 v[154:157], v166
	ds_read_b128 v[158:161], v166 offset:1024
	ds_read_b128 v[162:165], v166 offset:2048
	ds_read_b128 v[166:169], v166 offset:3072
	s_add_i32 s61, s37, s58
	s_add_i32 s60, s33, s58
	s_add_i32 s59, s61, 0x400
	s_addk_i32 s60, 0x400
	s_cmp_eq_u32 s58, 0
	s_cselect_b32 s62, s53, s59
	s_cselect_b32 s60, s54, s60
	s_or_b32 s59, s62, 0x80
	ds_read_b128 v[170:173], v9
	ds_read_b128 v[174:177], v9 offset:1024
	ds_read_b128 v[178:181], v9 offset:2048
	ds_read_b128 v[182:185], v9 offset:3072
	ds_read_b128 v[186:189], v9 offset:4096
	ds_read_b128 v[190:193], v9 offset:5120
	ds_read_b128 v[194:197], v9 offset:6144
	ds_read_b128 v[198:201], v9 offset:7168
	s_add_i32 s61, s61, 0x20380
	s_mov_b32 m0, s48
	s_nop 0
	buffer_load_dwordx4 v6, s[12:15], s61 offen lds
	s_nop 0
	s_mov_b32 m0, s49
	s_nop 0
	buffer_load_dwordx4 v7, s[12:15], s61 offen lds
	s_waitcnt vmcnt(8)
	s_waitcnt lgkmcnt(0)
	s_barrier
	s_waitcnt lgkmcnt(7)
	v_mfma_i32_16x16x64_i8 v[142:145], v[10:13], v[170:173], v[142:145]
	v_mfma_i32_16x16x64_i8 v[138:141], v[146:149], v[170:173], v[138:141]
	s_waitcnt lgkmcnt(5)
	v_mfma_i32_16x16x64_i8 v[126:129], v[10:13], v[178:181], v[126:129]
	v_mfma_i32_16x16x64_i8 v[122:125], v[146:149], v[178:181], v[122:125]
	s_waitcnt lgkmcnt(3)
	v_mfma_i32_16x16x64_i8 v[110:113], v[10:13], v[186:189], v[110:113]
	v_mfma_i32_16x16x64_i8 v[106:109], v[146:149], v[186:189], v[106:109]
	s_waitcnt lgkmcnt(1)
	v_mfma_i32_16x16x64_i8 v[94:97], v[10:13], v[194:197], v[94:97]
	v_mfma_i32_16x16x64_i8 v[90:93], v[146:149], v[194:197], v[90:93]
	v_mfma_i32_16x16x64_i8 v[142:145], v[14:17], v[174:177], v[142:145]
	v_mfma_i32_16x16x64_i8 v[138:141], v[150:153], v[174:177], v[138:141]
	v_mfma_i32_16x16x64_i8 v[126:129], v[14:17], v[182:185], v[126:129]
	v_mfma_i32_16x16x64_i8 v[122:125], v[150:153], v[182:185], v[122:125]
	v_mfma_i32_16x16x64_i8 v[110:113], v[14:17], v[190:193], v[110:113]
	v_mfma_i32_16x16x64_i8 v[106:109], v[150:153], v[190:193], v[106:109]
	s_waitcnt lgkmcnt(0)
	v_mfma_i32_16x16x64_i8 v[94:97], v[14:17], v[198:201], v[94:97]
	v_mfma_i32_16x16x64_i8 v[90:93], v[150:153], v[198:201], v[90:93]
	v_mfma_i32_16x16x64_i8 v[134:137], v[154:157], v[170:173], v[134:137]
	v_mfma_i32_16x16x64_i8 v[130:133], v[162:165], v[170:173], v[130:133]
	v_mfma_i32_16x16x64_i8 v[118:121], v[154:157], v[178:181], v[118:121]
	v_mfma_i32_16x16x64_i8 v[114:117], v[162:165], v[178:181], v[114:117]
	v_mfma_i32_16x16x64_i8 v[102:105], v[154:157], v[186:189], v[102:105]
	v_mfma_i32_16x16x64_i8 v[98:101], v[162:165], v[186:189], v[98:101]
	v_mfma_i32_16x16x64_i8 v[86:89], v[154:157], v[194:197], v[86:89]
	v_mfma_i32_16x16x64_i8 v[82:85], v[162:165], v[194:197], v[82:85]
	v_mfma_i32_16x16x64_i8 v[134:137], v[158:161], v[174:177], v[134:137]
	v_mfma_i32_16x16x64_i8 v[130:133], v[166:169], v[174:177], v[130:133]
	v_mfma_i32_16x16x64_i8 v[118:121], v[158:161], v[182:185], v[118:121]
	v_mfma_i32_16x16x64_i8 v[114:117], v[166:169], v[182:185], v[114:117]
	v_mfma_i32_16x16x64_i8 v[102:105], v[158:161], v[190:193], v[102:105]
	v_mfma_i32_16x16x64_i8 v[98:101], v[166:169], v[190:193], v[98:101]
	v_mfma_i32_16x16x64_i8 v[86:89], v[158:161], v[198:201], v[86:89]
	v_mfma_i32_16x16x64_i8 v[82:85], v[166:169], v[198:201], v[82:85]
	s_barrier
	ds_read_b128 v[170:173], v9 offset:16384
	ds_read_b128 v[174:177], v9 offset:17408
	ds_read_b128 v[178:181], v9 offset:18432
	ds_read_b128 v[182:185], v9 offset:19456
	ds_read_b128 v[186:189], v9 offset:20480
	ds_read_b128 v[190:193], v9 offset:21504
	ds_read_b128 v[194:197], v9 offset:22528
	ds_read_b128 v[198:201], v9 offset:23552
	s_mov_b32 m0, s29
	s_nop 0
	buffer_load_dwordx4 v6, s[8:11], s60 offen lds
	s_add_i32 s61, s60, 0x20000
	s_mov_b32 m0, s34
	s_nop 0
	buffer_load_dwordx4 v7, s[8:11], s60 offen lds
	s_nop 0
	s_mov_b32 m0, s35
	s_nop 0
	buffer_load_dwordx4 v6, s[8:11], s61 offen lds
	s_nop 0
	s_mov_b32 m0, s36
	s_nop 0
	buffer_load_dwordx4 v7, s[8:11], s61 offen lds
	s_nop 0
	s_mov_b32 m0, s28
	s_nop 0
	buffer_load_dwordx4 v6, s[12:15], s62 offen lds
	s_nop 0
	s_mov_b32 m0, s38
	s_nop 0
	buffer_load_dwordx4 v7, s[12:15], s62 offen lds
	s_waitcnt vmcnt(8)
	s_waitcnt lgkmcnt(0)
	s_barrier
	s_waitcnt lgkmcnt(7)
	v_mfma_i32_16x16x64_i8 v[78:81], v[10:13], v[170:173], v[78:81]
	v_mfma_i32_16x16x64_i8 v[74:77], v[146:149], v[170:173], v[74:77]
	s_waitcnt lgkmcnt(5)
	v_mfma_i32_16x16x64_i8 v[62:65], v[10:13], v[178:181], v[62:65]
	v_mfma_i32_16x16x64_i8 v[58:61], v[146:149], v[178:181], v[58:61]
	s_waitcnt lgkmcnt(3)
	v_mfma_i32_16x16x64_i8 v[46:49], v[10:13], v[186:189], v[46:49]
	v_mfma_i32_16x16x64_i8 v[42:45], v[146:149], v[186:189], v[42:45]
	s_waitcnt lgkmcnt(1)
	v_mfma_i32_16x16x64_i8 v[10:13], v[10:13], v[194:197], v[30:33]
	v_mfma_i32_16x16x64_i8 v[78:81], v[14:17], v[174:177], v[78:81]
	v_mfma_i32_16x16x64_i8 v[74:77], v[150:153], v[174:177], v[74:77]
	v_mfma_i32_16x16x64_i8 v[62:65], v[14:17], v[182:185], v[62:65]
	v_mfma_i32_16x16x64_i8 v[58:61], v[150:153], v[182:185], v[58:61]
	v_mfma_i32_16x16x64_i8 v[46:49], v[14:17], v[190:193], v[46:49]
	v_mfma_i32_16x16x64_i8 v[42:45], v[150:153], v[190:193], v[42:45]
	s_waitcnt lgkmcnt(0)
	v_mfma_i32_16x16x64_i8 v[10:13], v[14:17], v[198:201], v[10:13]
	v_mfma_i32_16x16x64_i8 v[14:17], v[146:149], v[194:197], v[26:29]
	v_mfma_i32_16x16x64_i8 v[14:17], v[150:153], v[198:201], v[14:17]
	v_mfma_i32_16x16x64_i8 v[26:29], v[154:157], v[170:173], v[70:73]
	v_mfma_i32_16x16x64_i8 v[70:73], v[158:161], v[174:177], v[26:29]
	v_mfma_i32_16x16x64_i8 v[26:29], v[162:165], v[170:173], v[66:69]
	v_mfma_i32_16x16x64_i8 v[66:69], v[166:169], v[174:177], v[26:29]
	v_mfma_i32_16x16x64_i8 v[26:29], v[154:157], v[178:181], v[54:57]
	v_mfma_i32_16x16x64_i8 v[54:57], v[158:161], v[182:185], v[26:29]
	v_mfma_i32_16x16x64_i8 v[26:29], v[162:165], v[178:181], v[50:53]
	v_mfma_i32_16x16x64_i8 v[50:53], v[166:169], v[182:185], v[26:29]
	v_mfma_i32_16x16x64_i8 v[26:29], v[154:157], v[186:189], v[38:41]
	v_mfma_i32_16x16x64_i8 v[38:41], v[158:161], v[190:193], v[26:29]
	v_mfma_i32_16x16x64_i8 v[26:29], v[162:165], v[186:189], v[34:37]
	v_mfma_i32_16x16x64_i8 v[22:25], v[154:157], v[194:197], v[22:25]
	v_mfma_i32_16x16x64_i8 v[18:21], v[162:165], v[194:197], v[18:21]
	v_mfma_i32_16x16x64_i8 v[34:37], v[166:169], v[190:193], v[26:29]
	v_mfma_i32_16x16x64_i8 v[22:25], v[158:161], v[198:201], v[22:25]
	v_mfma_i32_16x16x64_i8 v[18:21], v[166:169], v[198:201], v[18:21]
	s_barrier
	v_add_u32_e32 v150, 0x18000, v8
	v_add_u32_e32 v166, 0x1c000, v8
	ds_read_b128 v[26:29], v150
	ds_read_b128 v[30:33], v150 offset:1024
	ds_read_b128 v[146:149], v150 offset:2048
	ds_read_b128 v[150:153], v150 offset:3072
	ds_read_b128 v[154:157], v166
	ds_read_b128 v[158:161], v166 offset:1024
	ds_read_b128 v[162:165], v166 offset:2048
	ds_read_b128 v[166:169], v166 offset:3072
	ds_read_b128 v[170:173], v9 offset:32768
	ds_read_b128 v[174:177], v9 offset:33792
	ds_read_b128 v[178:181], v9 offset:34816
	ds_read_b128 v[182:185], v9 offset:35840
	ds_read_b128 v[186:189], v9 offset:36864
	ds_read_b128 v[190:193], v9 offset:37888
	ds_read_b128 v[194:197], v9 offset:38912
	ds_read_b128 v[198:201], v9 offset:39936
	s_add_i32 s61, s62, 0x20000
	s_mov_b32 m0, s40
	s_nop 0
	buffer_load_dwordx4 v6, s[12:15], s61 offen lds
	s_nop 0
	s_mov_b32 m0, s41
	s_nop 0
	buffer_load_dwordx4 v7, s[12:15], s61 offen lds
	s_waitcnt vmcnt(8)
	s_waitcnt lgkmcnt(0)
	s_barrier
	s_waitcnt lgkmcnt(7)
	v_mfma_i32_16x16x64_i8 v[142:145], v[26:29], v[170:173], v[142:145]
	v_mfma_i32_16x16x64_i8 v[138:141], v[146:149], v[170:173], v[138:141]
	s_waitcnt lgkmcnt(5)
	v_mfma_i32_16x16x64_i8 v[126:129], v[26:29], v[178:181], v[126:129]
	v_mfma_i32_16x16x64_i8 v[122:125], v[146:149], v[178:181], v[122:125]
	s_waitcnt lgkmcnt(3)
	v_mfma_i32_16x16x64_i8 v[110:113], v[26:29], v[186:189], v[110:113]
	v_mfma_i32_16x16x64_i8 v[106:109], v[146:149], v[186:189], v[106:109]
	s_waitcnt lgkmcnt(1)
	v_mfma_i32_16x16x64_i8 v[94:97], v[26:29], v[194:197], v[94:97]
	v_mfma_i32_16x16x64_i8 v[90:93], v[146:149], v[194:197], v[90:93]
	v_mfma_i32_16x16x64_i8 v[142:145], v[30:33], v[174:177], v[142:145]
	v_mfma_i32_16x16x64_i8 v[138:141], v[150:153], v[174:177], v[138:141]
	v_mfma_i32_16x16x64_i8 v[126:129], v[30:33], v[182:185], v[126:129]
	v_mfma_i32_16x16x64_i8 v[122:125], v[150:153], v[182:185], v[122:125]
	v_mfma_i32_16x16x64_i8 v[110:113], v[30:33], v[190:193], v[110:113]
	v_mfma_i32_16x16x64_i8 v[106:109], v[150:153], v[190:193], v[106:109]
	s_waitcnt lgkmcnt(0)
	v_mfma_i32_16x16x64_i8 v[94:97], v[30:33], v[198:201], v[94:97]
	v_mfma_i32_16x16x64_i8 v[90:93], v[150:153], v[198:201], v[90:93]
	v_mfma_i32_16x16x64_i8 v[134:137], v[154:157], v[170:173], v[134:137]
	v_mfma_i32_16x16x64_i8 v[130:133], v[162:165], v[170:173], v[130:133]
	v_mfma_i32_16x16x64_i8 v[118:121], v[154:157], v[178:181], v[118:121]
	v_mfma_i32_16x16x64_i8 v[114:117], v[162:165], v[178:181], v[114:117]
	v_mfma_i32_16x16x64_i8 v[102:105], v[154:157], v[186:189], v[102:105]
	v_mfma_i32_16x16x64_i8 v[98:101], v[162:165], v[186:189], v[98:101]
	v_mfma_i32_16x16x64_i8 v[86:89], v[154:157], v[194:197], v[86:89]
	v_mfma_i32_16x16x64_i8 v[82:85], v[162:165], v[194:197], v[82:85]
	v_mfma_i32_16x16x64_i8 v[134:137], v[158:161], v[174:177], v[134:137]
	v_mfma_i32_16x16x64_i8 v[130:133], v[166:169], v[174:177], v[130:133]
	v_mfma_i32_16x16x64_i8 v[118:121], v[158:161], v[182:185], v[118:121]
	v_mfma_i32_16x16x64_i8 v[114:117], v[166:169], v[182:185], v[114:117]
	v_mfma_i32_16x16x64_i8 v[102:105], v[158:161], v[190:193], v[102:105]
	v_mfma_i32_16x16x64_i8 v[98:101], v[166:169], v[190:193], v[98:101]
	v_mfma_i32_16x16x64_i8 v[86:89], v[158:161], v[198:201], v[86:89]
	v_mfma_i32_16x16x64_i8 v[82:85], v[166:169], v[198:201], v[82:85]
	s_barrier
	ds_read_b128 v[170:173], v9 offset:49152
	ds_read_b128 v[174:177], v9 offset:50176
	ds_read_b128 v[178:181], v9 offset:51200
	ds_read_b128 v[182:185], v9 offset:52224
	ds_read_b128 v[186:189], v9 offset:53248
	ds_read_b128 v[190:193], v9 offset:54272
	ds_read_b128 v[194:197], v9 offset:55296
	ds_read_b128 v[198:201], v9 offset:56320
	s_or_b32 s61, s60, 0x80
	s_mov_b32 m0, s42
	s_nop 0
	buffer_load_dwordx4 v6, s[8:11], s61 offen lds
	s_add_i32 s60, s60, 0x20080
	s_mov_b32 m0, s43
	s_nop 0
	buffer_load_dwordx4 v7, s[8:11], s61 offen lds
	s_nop 0
	s_mov_b32 m0, s46
	s_nop 0
	buffer_load_dwordx4 v6, s[8:11], s60 offen lds
	s_nop 0
	s_mov_b32 m0, s47
	s_nop 0
	buffer_load_dwordx4 v7, s[8:11], s60 offen lds
	s_nop 0
	s_mov_b32 m0, s44
	s_nop 0
	buffer_load_dwordx4 v6, s[12:15], s59 offen lds
	s_nop 0
	s_mov_b32 m0, s45
	s_nop 0
	buffer_load_dwordx4 v7, s[12:15], s59 offen lds
	s_waitcnt vmcnt(8)
	s_waitcnt lgkmcnt(0)
	s_barrier
	s_waitcnt lgkmcnt(7)
	v_mfma_i32_16x16x64_i8 v[78:81], v[26:29], v[170:173], v[78:81]
	s_waitcnt lgkmcnt(5)
	v_mfma_i32_16x16x64_i8 v[62:65], v[26:29], v[178:181], v[62:65]
	s_waitcnt lgkmcnt(3)
	v_mfma_i32_16x16x64_i8 v[46:49], v[26:29], v[186:189], v[46:49]
	s_waitcnt lgkmcnt(1)
	v_mfma_i32_16x16x64_i8 v[10:13], v[26:29], v[194:197], v[10:13]
	v_mfma_i32_16x16x64_i8 v[78:81], v[30:33], v[174:177], v[78:81]
	v_mfma_i32_16x16x64_i8 v[74:77], v[146:149], v[170:173], v[74:77]
	v_mfma_i32_16x16x64_i8 v[62:65], v[30:33], v[182:185], v[62:65]
	v_mfma_i32_16x16x64_i8 v[58:61], v[146:149], v[178:181], v[58:61]
	v_mfma_i32_16x16x64_i8 v[46:49], v[30:33], v[190:193], v[46:49]
	v_mfma_i32_16x16x64_i8 v[42:45], v[146:149], v[186:189], v[42:45]
	s_waitcnt lgkmcnt(0)
	v_mfma_i32_16x16x64_i8 v[30:33], v[30:33], v[198:201], v[10:13]
	v_mfma_i32_16x16x64_i8 v[10:13], v[146:149], v[194:197], v[14:17]
	v_mfma_i32_16x16x64_i8 v[74:77], v[150:153], v[174:177], v[74:77]
	v_mfma_i32_16x16x64_i8 v[58:61], v[150:153], v[182:185], v[58:61]
	v_mfma_i32_16x16x64_i8 v[42:45], v[150:153], v[190:193], v[42:45]
	v_mfma_i32_16x16x64_i8 v[26:29], v[150:153], v[198:201], v[10:13]
	v_mfma_i32_16x16x64_i8 v[10:13], v[154:157], v[170:173], v[70:73]
	v_mfma_i32_16x16x64_i8 v[70:73], v[158:161], v[174:177], v[10:13]
	v_mfma_i32_16x16x64_i8 v[10:13], v[162:165], v[170:173], v[66:69]
	v_mfma_i32_16x16x64_i8 v[66:69], v[166:169], v[174:177], v[10:13]
	v_mfma_i32_16x16x64_i8 v[10:13], v[154:157], v[178:181], v[54:57]
	v_mfma_i32_16x16x64_i8 v[54:57], v[158:161], v[182:185], v[10:13]
	v_mfma_i32_16x16x64_i8 v[10:13], v[162:165], v[178:181], v[50:53]
	v_mfma_i32_16x16x64_i8 v[50:53], v[166:169], v[182:185], v[10:13]
	v_mfma_i32_16x16x64_i8 v[10:13], v[154:157], v[186:189], v[38:41]
	v_mfma_i32_16x16x64_i8 v[38:41], v[158:161], v[190:193], v[10:13]
	v_mfma_i32_16x16x64_i8 v[10:13], v[162:165], v[186:189], v[34:37]
	v_mfma_i32_16x16x64_i8 v[34:37], v[166:169], v[190:193], v[10:13]
	v_mfma_i32_16x16x64_i8 v[10:13], v[154:157], v[194:197], v[22:25]
	v_mfma_i32_16x16x64_i8 v[22:25], v[158:161], v[198:201], v[10:13]
	v_mfma_i32_16x16x64_i8 v[10:13], v[162:165], v[194:197], v[18:21]
	v_mfma_i32_16x16x64_i8 v[18:21], v[166:169], v[198:201], v[10:13]
	s_barrier
	s_add_i32 s55, s55, 2
	s_addk_i32 s58, 0x100
	s_cmp_lt_u32 s55, 6
	s_cbranch_scc1 .LBB0_943
	s_andn2_b64 vcc, exec, s[6:7]
	s_cbranch_vccz .LBB0_935
	v_cvt_f32_i32_e32 v142, v142
	v_cvt_f32_i32_e32 v143, v143
	v_cvt_f32_i32_e32 v144, v144
	v_cvt_f32_i32_e32 v145, v145
	v_cvt_f32_i32_e32 v138, v138
	v_cvt_f32_i32_e32 v139, v139
	v_cvt_f32_i32_e32 v140, v140
	v_cvt_f32_i32_e32 v141, v141
	v_cvt_f32_i32_e32 v126, v126
	v_cvt_f32_i32_e32 v127, v127
	v_cvt_f32_i32_e32 v128, v128
	v_cvt_f32_i32_e32 v129, v129
	v_cvt_f32_i32_e32 v122, v122
	v_cvt_f32_i32_e32 v123, v123
	v_cvt_f32_i32_e32 v124, v124
	v_cvt_f32_i32_e32 v125, v125
	v_cvt_f32_i32_e32 v110, v110
	v_cvt_f32_i32_e32 v111, v111
	v_cvt_f32_i32_e32 v112, v112
	v_cvt_f32_i32_e32 v113, v113
	v_cvt_f32_i32_e32 v106, v106
	v_cvt_f32_i32_e32 v107, v107
	v_cvt_f32_i32_e32 v108, v108
	v_cvt_f32_i32_e32 v109, v109
	v_cvt_f32_i32_e32 v94, v94
	v_cvt_f32_i32_e32 v95, v95
	v_cvt_f32_i32_e32 v96, v96
	v_cvt_f32_i32_e32 v97, v97
	v_cvt_f32_i32_e32 v90, v90
	v_cvt_f32_i32_e32 v91, v91
	v_cvt_f32_i32_e32 v92, v92
	v_cvt_f32_i32_e32 v93, v93
	v_cvt_f32_i32_e32 v134, v134
	v_cvt_f32_i32_e32 v135, v135
	v_cvt_f32_i32_e32 v136, v136
	v_cvt_f32_i32_e32 v137, v137
	v_cvt_f32_i32_e32 v130, v130
	v_cvt_f32_i32_e32 v131, v131
	v_cvt_f32_i32_e32 v132, v132
	v_cvt_f32_i32_e32 v133, v133
	v_cvt_f32_i32_e32 v118, v118
	v_cvt_f32_i32_e32 v119, v119
	v_cvt_f32_i32_e32 v120, v120
	v_cvt_f32_i32_e32 v121, v121
	v_cvt_f32_i32_e32 v114, v114
	v_cvt_f32_i32_e32 v115, v115
	v_cvt_f32_i32_e32 v116, v116
	v_cvt_f32_i32_e32 v117, v117
	v_cvt_f32_i32_e32 v102, v102
	v_cvt_f32_i32_e32 v103, v103
	v_cvt_f32_i32_e32 v104, v104
	v_cvt_f32_i32_e32 v105, v105
	v_cvt_f32_i32_e32 v98, v98
	v_cvt_f32_i32_e32 v99, v99
	v_cvt_f32_i32_e32 v100, v100
	v_cvt_f32_i32_e32 v101, v101
	v_cvt_f32_i32_e32 v86, v86
	v_cvt_f32_i32_e32 v87, v87
	v_cvt_f32_i32_e32 v88, v88
	v_cvt_f32_i32_e32 v89, v89
	v_cvt_f32_i32_e32 v82, v82
	v_cvt_f32_i32_e32 v83, v83
	v_cvt_f32_i32_e32 v84, v84
	v_cvt_f32_i32_e32 v85, v85
	v_cvt_f32_i32_e32 v78, v78
	v_cvt_f32_i32_e32 v79, v79
	v_cvt_f32_i32_e32 v80, v80
	v_cvt_f32_i32_e32 v81, v81
	v_cvt_f32_i32_e32 v74, v74
	v_cvt_f32_i32_e32 v75, v75
	v_cvt_f32_i32_e32 v76, v76
	v_cvt_f32_i32_e32 v77, v77
	v_cvt_f32_i32_e32 v62, v62
	v_cvt_f32_i32_e32 v63, v63
	v_cvt_f32_i32_e32 v64, v64
	v_cvt_f32_i32_e32 v65, v65
	v_cvt_f32_i32_e32 v58, v58
	v_cvt_f32_i32_e32 v59, v59
	v_cvt_f32_i32_e32 v60, v60
	v_cvt_f32_i32_e32 v61, v61
	v_cvt_f32_i32_e32 v46, v46
	v_cvt_f32_i32_e32 v47, v47
	v_cvt_f32_i32_e32 v48, v48
	v_cvt_f32_i32_e32 v49, v49
	v_cvt_f32_i32_e32 v42, v42
	v_cvt_f32_i32_e32 v43, v43
	v_cvt_f32_i32_e32 v44, v44
	v_cvt_f32_i32_e32 v45, v45
	v_cvt_f32_i32_e32 v30, v30
	v_cvt_f32_i32_e32 v31, v31
	v_cvt_f32_i32_e32 v32, v32
	v_cvt_f32_i32_e32 v33, v33
	v_cvt_f32_i32_e32 v26, v26
	v_cvt_f32_i32_e32 v27, v27
	v_cvt_f32_i32_e32 v28, v28
	v_cvt_f32_i32_e32 v29, v29
	v_cvt_f32_i32_e32 v70, v70
	v_cvt_f32_i32_e32 v71, v71
	v_cvt_f32_i32_e32 v72, v72
	v_cvt_f32_i32_e32 v73, v73
	v_cvt_f32_i32_e32 v66, v66
	v_cvt_f32_i32_e32 v67, v67
	v_cvt_f32_i32_e32 v68, v68
	v_cvt_f32_i32_e32 v69, v69
	v_cvt_f32_i32_e32 v54, v54
	v_cvt_f32_i32_e32 v55, v55
	v_cvt_f32_i32_e32 v56, v56
	v_cvt_f32_i32_e32 v57, v57
	v_cvt_f32_i32_e32 v50, v50
	v_cvt_f32_i32_e32 v51, v51
	v_cvt_f32_i32_e32 v52, v52
	v_cvt_f32_i32_e32 v53, v53
	v_cvt_f32_i32_e32 v38, v38
	v_cvt_f32_i32_e32 v39, v39
	v_cvt_f32_i32_e32 v40, v40
	v_cvt_f32_i32_e32 v41, v41
	v_cvt_f32_i32_e32 v34, v34
	v_cvt_f32_i32_e32 v35, v35
	v_cvt_f32_i32_e32 v36, v36
	v_cvt_f32_i32_e32 v37, v37
	v_cvt_f32_i32_e32 v22, v22
	v_cvt_f32_i32_e32 v23, v23
	v_cvt_f32_i32_e32 v24, v24
	v_cvt_f32_i32_e32 v25, v25
	v_cvt_f32_i32_e32 v18, v18
	v_cvt_f32_i32_e32 v19, v19
	v_cvt_f32_i32_e32 v20, v20
	v_cvt_f32_i32_e32 v21, v21
	s_andn2_b64 vcc, exec, s[4:5]
	s_cbranch_vccnz .LBB0_936

.LBB0_1072:
	ds_read_b128 v[136:139], v152
	ds_read_b128 v[140:143], v152 offset:1024
	ds_read_b128 v[158:161], v152 offset:2048
	ds_read_b128 v[162:165], v152 offset:3072
	ds_read_b128 v[166:169], v153
	ds_read_b128 v[170:173], v153 offset:1024
	ds_read_b128 v[174:177], v153 offset:2048
	ds_read_b128 v[178:181], v153 offset:3072
	s_add_i32 s60, s55, 0xfffe0080
	s_cmp_eq_u32 s59, 4
	s_cselect_b32 s62, s1, s60
	s_cselect_b32 s61, s54, s58
	s_or_b32 s60, s62, 0x80
	ds_read_b128 v[182:185], v154
	ds_read_b128 v[186:189], v154 offset:1024
	ds_read_b128 v[190:193], v154 offset:2048
	ds_read_b128 v[194:197], v154 offset:3072
	ds_read_b128 v[198:201], v154 offset:4096
	ds_read_b128 v[202:205], v154 offset:5120
	ds_read_b128 v[206:209], v154 offset:6144
	ds_read_b128 v[210:213], v154 offset:7168
	s_mov_b32 m0, s42
	s_nop 0
	buffer_load_dwordx4 v146, s[12:15], s55 offen lds
	s_nop 0
	s_mov_b32 m0, s43
	s_nop 0
	buffer_load_dwordx4 v147, s[12:15], s55 offen lds
	s_waitcnt vmcnt(8)
	s_waitcnt lgkmcnt(0)
	s_barrier
	s_waitcnt lgkmcnt(0)
	v_mfma_i32_16x16x64_i8 v[126:129], v[136:139], v[182:185], v[126:129]
	v_mfma_i32_16x16x64_i8 v[122:125], v[158:161], v[182:185], v[122:125]
	v_mfma_i32_16x16x64_i8 v[118:121], v[136:139], v[190:193], v[118:121]
	v_mfma_i32_16x16x64_i8 v[114:117], v[158:161], v[190:193], v[114:117]
	v_mfma_i32_16x16x64_i8 v[110:113], v[136:139], v[198:201], v[110:113]
	v_mfma_i32_16x16x64_i8 v[106:109], v[158:161], v[198:201], v[106:109]
	v_mfma_i32_16x16x64_i8 v[102:105], v[136:139], v[206:209], v[102:105]
	v_mfma_i32_16x16x64_i8 v[98:101], v[158:161], v[206:209], v[98:101]
	v_mfma_i32_16x16x64_i8 v[126:129], v[140:143], v[186:189], v[126:129]
	v_mfma_i32_16x16x64_i8 v[122:125], v[162:165], v[186:189], v[122:125]
	v_mfma_i32_16x16x64_i8 v[118:121], v[140:143], v[194:197], v[118:121]
	v_mfma_i32_16x16x64_i8 v[114:117], v[162:165], v[194:197], v[114:117]
	v_mfma_i32_16x16x64_i8 v[110:113], v[140:143], v[202:205], v[110:113]
	v_mfma_i32_16x16x64_i8 v[106:109], v[162:165], v[202:205], v[106:109]
	v_mfma_i32_16x16x64_i8 v[102:105], v[140:143], v[210:213], v[102:105]
	v_mfma_i32_16x16x64_i8 v[98:101], v[162:165], v[210:213], v[98:101]
	v_mfma_i32_16x16x64_i8 v[94:97], v[166:169], v[182:185], v[94:97]
	v_mfma_i32_16x16x64_i8 v[90:93], v[174:177], v[182:185], v[90:93]
	v_mfma_i32_16x16x64_i8 v[86:89], v[166:169], v[190:193], v[86:89]
	v_mfma_i32_16x16x64_i8 v[82:85], v[174:177], v[190:193], v[82:85]
	v_mfma_i32_16x16x64_i8 v[78:81], v[166:169], v[198:201], v[78:81]
	v_mfma_i32_16x16x64_i8 v[74:77], v[174:177], v[198:201], v[74:77]
	v_mfma_i32_16x16x64_i8 v[70:73], v[166:169], v[206:209], v[70:73]
	v_mfma_i32_16x16x64_i8 v[66:69], v[174:177], v[206:209], v[66:69]
	v_mfma_i32_16x16x64_i8 v[94:97], v[170:173], v[186:189], v[94:97]
	v_mfma_i32_16x16x64_i8 v[90:93], v[178:181], v[186:189], v[90:93]
	v_mfma_i32_16x16x64_i8 v[86:89], v[170:173], v[194:197], v[86:89]
	v_mfma_i32_16x16x64_i8 v[82:85], v[178:181], v[194:197], v[82:85]
	v_mfma_i32_16x16x64_i8 v[78:81], v[170:173], v[202:205], v[78:81]
	v_mfma_i32_16x16x64_i8 v[74:77], v[178:181], v[202:205], v[74:77]
	v_mfma_i32_16x16x64_i8 v[70:73], v[170:173], v[210:213], v[70:73]
	v_mfma_i32_16x16x64_i8 v[66:69], v[178:181], v[210:213], v[66:69]
	s_barrier
	ds_read_b128 v[182:185], v154 offset:16384
	ds_read_b128 v[186:189], v154 offset:17408
	ds_read_b128 v[190:193], v154 offset:18432
	ds_read_b128 v[194:197], v154 offset:19456
	ds_read_b128 v[198:201], v154 offset:20480
	ds_read_b128 v[202:205], v154 offset:21504
	ds_read_b128 v[206:209], v154 offset:22528
	ds_read_b128 v[210:213], v154 offset:23552
	s_mov_b32 m0, s27
	s_nop 0
	buffer_load_dwordx4 v144, s[8:11], s61 offen lds
	s_add_i32 s63, s61, 0x20000
	s_mov_b32 m0, s28
	s_nop 0
	buffer_load_dwordx4 v145, s[8:11], s61 offen lds
	s_nop 0
	s_mov_b32 m0, s29
	s_nop 0
	buffer_load_dwordx4 v144, s[8:11], s63 offen lds
	s_nop 0
	s_mov_b32 m0, s30
	s_nop 0
	buffer_load_dwordx4 v145, s[8:11], s63 offen lds
	s_nop 0
	s_mov_b32 m0, s26
	s_nop 0
	buffer_load_dwordx4 v146, s[12:15], s62 offen lds
	s_nop 0
	s_mov_b32 m0, s2
	s_nop 0
	buffer_load_dwordx4 v147, s[12:15], s62 offen lds
	s_waitcnt vmcnt(8)
	s_waitcnt lgkmcnt(0)
	s_barrier
	s_waitcnt lgkmcnt(0)
	v_mfma_i32_16x16x64_i8 v[62:65], v[136:139], v[182:185], v[62:65]
	v_mfma_i32_16x16x64_i8 v[58:61], v[158:161], v[182:185], v[58:61]
	v_mfma_i32_16x16x64_i8 v[54:57], v[136:139], v[190:193], v[54:57]
	v_mfma_i32_16x16x64_i8 v[50:53], v[158:161], v[190:193], v[50:53]
	v_mfma_i32_16x16x64_i8 v[46:49], v[136:139], v[198:201], v[46:49]
	v_mfma_i32_16x16x64_i8 v[42:45], v[158:161], v[198:201], v[42:45]
	v_mfma_i32_16x16x64_i8 v[38:41], v[136:139], v[206:209], v[38:41]
	v_mfma_i32_16x16x64_i8 v[34:37], v[158:161], v[206:209], v[34:37]
	v_mfma_i32_16x16x64_i8 v[62:65], v[140:143], v[186:189], v[62:65]
	v_mfma_i32_16x16x64_i8 v[58:61], v[162:165], v[186:189], v[58:61]
	v_mfma_i32_16x16x64_i8 v[54:57], v[140:143], v[194:197], v[54:57]
	v_mfma_i32_16x16x64_i8 v[50:53], v[162:165], v[194:197], v[50:53]
	v_mfma_i32_16x16x64_i8 v[46:49], v[140:143], v[202:205], v[46:49]
	v_mfma_i32_16x16x64_i8 v[42:45], v[162:165], v[202:205], v[42:45]
	v_mfma_i32_16x16x64_i8 v[38:41], v[140:143], v[210:213], v[38:41]
	v_mfma_i32_16x16x64_i8 v[34:37], v[162:165], v[210:213], v[34:37]
	v_mfma_i32_16x16x64_i8 v[30:33], v[166:169], v[182:185], v[30:33]
	v_mfma_i32_16x16x64_i8 v[26:29], v[174:177], v[182:185], v[26:29]
	v_mfma_i32_16x16x64_i8 v[22:25], v[166:169], v[190:193], v[22:25]
	v_mfma_i32_16x16x64_i8 v[18:21], v[174:177], v[190:193], v[18:21]
	v_mfma_i32_16x16x64_i8 v[14:17], v[166:169], v[198:201], v[14:17]
	v_mfma_i32_16x16x64_i8 v[10:13], v[174:177], v[198:201], v[10:13]
	v_mfma_i32_16x16x64_i8 v[6:9], v[166:169], v[206:209], v[6:9]
	v_mfma_i32_16x16x64_i8 v[2:5], v[174:177], v[206:209], v[2:5]
	v_mfma_i32_16x16x64_i8 v[30:33], v[170:173], v[186:189], v[30:33]
	v_mfma_i32_16x16x64_i8 v[26:29], v[178:181], v[186:189], v[26:29]
	v_mfma_i32_16x16x64_i8 v[22:25], v[170:173], v[194:197], v[22:25]
	v_mfma_i32_16x16x64_i8 v[18:21], v[178:181], v[194:197], v[18:21]
	v_mfma_i32_16x16x64_i8 v[14:17], v[170:173], v[202:205], v[14:17]
	v_mfma_i32_16x16x64_i8 v[10:13], v[178:181], v[202:205], v[10:13]
	v_mfma_i32_16x16x64_i8 v[6:9], v[170:173], v[210:213], v[6:9]
	v_mfma_i32_16x16x64_i8 v[2:5], v[178:181], v[210:213], v[2:5]
	s_barrier
	ds_read_b128 v[136:139], v155
	ds_read_b128 v[140:143], v155 offset:1024
	ds_read_b128 v[158:161], v155 offset:2048
	ds_read_b128 v[162:165], v155 offset:3072
	ds_read_b128 v[166:169], v156
	ds_read_b128 v[170:173], v156 offset:1024
	ds_read_b128 v[174:177], v156 offset:2048
	ds_read_b128 v[178:181], v156 offset:3072
	ds_read_b128 v[182:185], v154 offset:32768
	ds_read_b128 v[186:189], v154 offset:33792
	ds_read_b128 v[190:193], v154 offset:34816
	ds_read_b128 v[194:197], v154 offset:35840
	ds_read_b128 v[198:201], v154 offset:36864
	ds_read_b128 v[202:205], v154 offset:37888
	ds_read_b128 v[206:209], v154 offset:38912
	ds_read_b128 v[210:213], v154 offset:39936
	s_add_i32 s62, s62, 0x20000
	s_mov_b32 m0, s3
	s_nop 0
	buffer_load_dwordx4 v146, s[12:15], s62 offen lds
	s_nop 0
	s_mov_b32 m0, s31
	s_nop 0
	buffer_load_dwordx4 v147, s[12:15], s62 offen lds
	s_waitcnt vmcnt(8)
	s_waitcnt lgkmcnt(0)
	s_barrier
	s_waitcnt lgkmcnt(0)
	v_mfma_i32_16x16x64_i8 v[126:129], v[136:139], v[182:185], v[126:129]
	v_mfma_i32_16x16x64_i8 v[122:125], v[158:161], v[182:185], v[122:125]
	v_mfma_i32_16x16x64_i8 v[118:121], v[136:139], v[190:193], v[118:121]
	v_mfma_i32_16x16x64_i8 v[114:117], v[158:161], v[190:193], v[114:117]
	v_mfma_i32_16x16x64_i8 v[110:113], v[136:139], v[198:201], v[110:113]
	v_mfma_i32_16x16x64_i8 v[106:109], v[158:161], v[198:201], v[106:109]
	v_mfma_i32_16x16x64_i8 v[102:105], v[136:139], v[206:209], v[102:105]
	v_mfma_i32_16x16x64_i8 v[98:101], v[158:161], v[206:209], v[98:101]
	v_mfma_i32_16x16x64_i8 v[126:129], v[140:143], v[186:189], v[126:129]
	v_mfma_i32_16x16x64_i8 v[122:125], v[162:165], v[186:189], v[122:125]
	v_mfma_i32_16x16x64_i8 v[118:121], v[140:143], v[194:197], v[118:121]
	v_mfma_i32_16x16x64_i8 v[114:117], v[162:165], v[194:197], v[114:117]
	v_mfma_i32_16x16x64_i8 v[110:113], v[140:143], v[202:205], v[110:113]
	v_mfma_i32_16x16x64_i8 v[106:109], v[162:165], v[202:205], v[106:109]
	v_mfma_i32_16x16x64_i8 v[102:105], v[140:143], v[210:213], v[102:105]
	v_mfma_i32_16x16x64_i8 v[98:101], v[162:165], v[210:213], v[98:101]
	v_mfma_i32_16x16x64_i8 v[94:97], v[166:169], v[182:185], v[94:97]
	v_mfma_i32_16x16x64_i8 v[90:93], v[174:177], v[182:185], v[90:93]
	v_mfma_i32_16x16x64_i8 v[86:89], v[166:169], v[190:193], v[86:89]
	v_mfma_i32_16x16x64_i8 v[82:85], v[174:177], v[190:193], v[82:85]
	v_mfma_i32_16x16x64_i8 v[78:81], v[166:169], v[198:201], v[78:81]
	v_mfma_i32_16x16x64_i8 v[74:77], v[174:177], v[198:201], v[74:77]
	v_mfma_i32_16x16x64_i8 v[70:73], v[166:169], v[206:209], v[70:73]
	v_mfma_i32_16x16x64_i8 v[66:69], v[174:177], v[206:209], v[66:69]
	v_mfma_i32_16x16x64_i8 v[94:97], v[170:173], v[186:189], v[94:97]
	v_mfma_i32_16x16x64_i8 v[90:93], v[178:181], v[186:189], v[90:93]
	v_mfma_i32_16x16x64_i8 v[86:89], v[170:173], v[194:197], v[86:89]
	v_mfma_i32_16x16x64_i8 v[82:85], v[178:181], v[194:197], v[82:85]
	v_mfma_i32_16x16x64_i8 v[78:81], v[170:173], v[202:205], v[78:81]
	v_mfma_i32_16x16x64_i8 v[74:77], v[178:181], v[202:205], v[74:77]
	v_mfma_i32_16x16x64_i8 v[70:73], v[170:173], v[210:213], v[70:73]
	v_mfma_i32_16x16x64_i8 v[66:69], v[178:181], v[210:213], v[66:69]
	s_barrier
	ds_read_b128 v[182:185], v154 offset:49152
	ds_read_b128 v[186:189], v154 offset:50176
	ds_read_b128 v[190:193], v154 offset:51200
	ds_read_b128 v[194:197], v154 offset:52224
	ds_read_b128 v[198:201], v154 offset:53248
	ds_read_b128 v[202:205], v154 offset:54272
	ds_read_b128 v[206:209], v154 offset:55296
	ds_read_b128 v[210:213], v154 offset:56320
	s_or_b32 s62, s61, 0x80
	s_mov_b32 m0, s35
	s_nop 0
	buffer_load_dwordx4 v144, s[8:11], s62 offen lds
	s_add_i32 s61, s61, 0x20080
	s_mov_b32 m0, s36
	s_nop 0
	buffer_load_dwordx4 v145, s[8:11], s62 offen lds
	s_nop 0
	s_mov_b32 m0, s39
	s_nop 0
	buffer_load_dwordx4 v144, s[8:11], s61 offen lds
	s_nop 0
	s_mov_b32 m0, s40
	s_nop 0
	buffer_load_dwordx4 v145, s[8:11], s61 offen lds
	s_nop 0
	s_mov_b32 m0, s37
	s_nop 0
	buffer_load_dwordx4 v146, s[12:15], s60 offen lds
	s_nop 0
	s_mov_b32 m0, s38
	s_nop 0
	buffer_load_dwordx4 v147, s[12:15], s60 offen lds
	s_waitcnt vmcnt(8)
	s_waitcnt lgkmcnt(0)
	s_barrier
	s_waitcnt lgkmcnt(0)
	v_mfma_i32_16x16x64_i8 v[62:65], v[136:139], v[182:185], v[62:65]
	v_mfma_i32_16x16x64_i8 v[58:61], v[158:161], v[182:185], v[58:61]
	v_mfma_i32_16x16x64_i8 v[54:57], v[136:139], v[190:193], v[54:57]
	v_mfma_i32_16x16x64_i8 v[50:53], v[158:161], v[190:193], v[50:53]
	v_mfma_i32_16x16x64_i8 v[46:49], v[136:139], v[198:201], v[46:49]
	v_mfma_i32_16x16x64_i8 v[42:45], v[158:161], v[198:201], v[42:45]
	v_mfma_i32_16x16x64_i8 v[38:41], v[136:139], v[206:209], v[38:41]
	v_mfma_i32_16x16x64_i8 v[34:37], v[158:161], v[206:209], v[34:37]
	v_mfma_i32_16x16x64_i8 v[62:65], v[140:143], v[186:189], v[62:65]
	v_mfma_i32_16x16x64_i8 v[58:61], v[162:165], v[186:189], v[58:61]
	v_mfma_i32_16x16x64_i8 v[54:57], v[140:143], v[194:197], v[54:57]
	v_mfma_i32_16x16x64_i8 v[50:53], v[162:165], v[194:197], v[50:53]
	v_mfma_i32_16x16x64_i8 v[46:49], v[140:143], v[202:205], v[46:49]
	v_mfma_i32_16x16x64_i8 v[42:45], v[162:165], v[202:205], v[42:45]
	v_mfma_i32_16x16x64_i8 v[38:41], v[140:143], v[210:213], v[38:41]
	v_mfma_i32_16x16x64_i8 v[34:37], v[162:165], v[210:213], v[34:37]
	v_mfma_i32_16x16x64_i8 v[30:33], v[166:169], v[182:185], v[30:33]
	v_mfma_i32_16x16x64_i8 v[26:29], v[174:177], v[182:185], v[26:29]
	v_mfma_i32_16x16x64_i8 v[22:25], v[166:169], v[190:193], v[22:25]
	v_mfma_i32_16x16x64_i8 v[18:21], v[174:177], v[190:193], v[18:21]
	v_mfma_i32_16x16x64_i8 v[14:17], v[166:169], v[198:201], v[14:17]
	v_mfma_i32_16x16x64_i8 v[10:13], v[174:177], v[198:201], v[10:13]
	v_mfma_i32_16x16x64_i8 v[6:9], v[166:169], v[206:209], v[6:9]
	v_mfma_i32_16x16x64_i8 v[2:5], v[174:177], v[206:209], v[2:5]
	v_mfma_i32_16x16x64_i8 v[30:33], v[170:173], v[186:189], v[30:33]
	v_mfma_i32_16x16x64_i8 v[26:29], v[178:181], v[186:189], v[26:29]
	v_mfma_i32_16x16x64_i8 v[22:25], v[170:173], v[194:197], v[22:25]
	v_mfma_i32_16x16x64_i8 v[18:21], v[178:181], v[194:197], v[18:21]
	v_mfma_i32_16x16x64_i8 v[14:17], v[170:173], v[202:205], v[14:17]
	v_mfma_i32_16x16x64_i8 v[10:13], v[178:181], v[202:205], v[10:13]
	v_mfma_i32_16x16x64_i8 v[6:9], v[170:173], v[210:213], v[6:9]
	v_mfma_i32_16x16x64_i8 v[2:5], v[178:181], v[210:213], v[2:5]
	s_barrier
	s_add_i32 s59, s59, 2
	s_addk_i32 s55, 0x100
	s_addk_i32 s58, 0x100
	s_cmp_gt_u32 s59, 5
	s_cbranch_scc0 .LBB0_1072
	s_and_b64 vcc, exec, s[20:21]
	s_cbranch_vccz .LBB0_1075
	s_barrier

.LBB0_1135:
	v_add_u32_e32 v150, 0x10000, v136
	v_add_u32_e32 v166, 0x14000, v136
	ds_read_b128 v[138:141], v150
	ds_read_b128 v[142:145], v150 offset:1024
	ds_read_b128 v[146:149], v150 offset:2048
	ds_read_b128 v[150:153], v150 offset:3072
	ds_read_b128 v[154:157], v166
	ds_read_b128 v[158:161], v166 offset:1024
	ds_read_b128 v[162:165], v166 offset:2048
	ds_read_b128 v[166:169], v166 offset:3072
	s_add_i32 s57, s36, s3
	s_add_i32 s56, s30, s3
	s_add_i32 s55, s57, 0x1600
	s_addk_i32 s56, 0x1600
	s_cmp_eq_u32 s3, 0
	s_cselect_b32 s58, s53, s55
	s_cselect_b32 s56, s54, s56
	s_add_i32 s55, s58, 0x80
	ds_read_b128 v[170:173], v137
	ds_read_b128 v[174:177], v137 offset:1024
	ds_read_b128 v[178:181], v137 offset:2048
	ds_read_b128 v[182:185], v137 offset:3072
	ds_read_b128 v[186:189], v137 offset:4096
	ds_read_b128 v[190:193], v137 offset:5120
	ds_read_b128 v[194:197], v137 offset:6144
	ds_read_b128 v[198:201], v137 offset:7168
	s_add_i32 s57, s57, 0xb1580
	s_mov_b32 m0, s46
	s_nop 0
	buffer_load_dwordx4 v134, s[16:19], s57 offen lds
	s_nop 0
	s_mov_b32 m0, s47
	s_nop 0
	buffer_load_dwordx4 v135, s[16:19], s57 offen lds
	s_waitcnt vmcnt(8)
	s_waitcnt lgkmcnt(0)
	s_barrier
	s_waitcnt lgkmcnt(7)
	v_mfma_f32_16x16x32_bf16 v[126:129], v[138:141], v[170:173], v[126:129]
	v_mfma_f32_16x16x32_bf16 v[122:125], v[146:149], v[170:173], v[122:125]
	s_waitcnt lgkmcnt(5)
	v_mfma_f32_16x16x32_bf16 v[118:121], v[138:141], v[178:181], v[118:121]
	v_mfma_f32_16x16x32_bf16 v[106:109], v[146:149], v[178:181], v[106:109]
	s_waitcnt lgkmcnt(3)
	v_mfma_f32_16x16x32_bf16 v[102:105], v[138:141], v[186:189], v[102:105]
	v_mfma_f32_16x16x32_bf16 v[90:93], v[146:149], v[186:189], v[90:93]
	s_waitcnt lgkmcnt(1)
	v_mfma_f32_16x16x32_bf16 v[86:89], v[138:141], v[194:197], v[86:89]
	v_mfma_f32_16x16x32_bf16 v[74:77], v[146:149], v[194:197], v[74:77]
	v_mfma_f32_16x16x32_bf16 v[126:129], v[142:145], v[174:177], v[126:129]
	v_mfma_f32_16x16x32_bf16 v[122:125], v[150:153], v[174:177], v[122:125]
	v_mfma_f32_16x16x32_bf16 v[118:121], v[142:145], v[182:185], v[118:121]
	v_mfma_f32_16x16x32_bf16 v[106:109], v[150:153], v[182:185], v[106:109]
	v_mfma_f32_16x16x32_bf16 v[102:105], v[142:145], v[190:193], v[102:105]
	v_mfma_f32_16x16x32_bf16 v[90:93], v[150:153], v[190:193], v[90:93]
	s_waitcnt lgkmcnt(0)
	v_mfma_f32_16x16x32_bf16 v[86:89], v[142:145], v[198:201], v[86:89]
	v_mfma_f32_16x16x32_bf16 v[74:77], v[150:153], v[198:201], v[74:77]
	v_mfma_f32_16x16x32_bf16 v[114:117], v[154:157], v[170:173], v[114:117]
	v_mfma_f32_16x16x32_bf16 v[110:113], v[162:165], v[170:173], v[110:113]
	v_mfma_f32_16x16x32_bf16 v[98:101], v[154:157], v[178:181], v[98:101]
	v_mfma_f32_16x16x32_bf16 v[94:97], v[162:165], v[178:181], v[94:97]
	v_mfma_f32_16x16x32_bf16 v[82:85], v[154:157], v[186:189], v[82:85]
	v_mfma_f32_16x16x32_bf16 v[78:81], v[162:165], v[186:189], v[78:81]
	v_mfma_f32_16x16x32_bf16 v[70:73], v[154:157], v[194:197], v[70:73]
	v_mfma_f32_16x16x32_bf16 v[66:69], v[162:165], v[194:197], v[66:69]
	v_mfma_f32_16x16x32_bf16 v[114:117], v[158:161], v[174:177], v[114:117]
	v_mfma_f32_16x16x32_bf16 v[110:113], v[166:169], v[174:177], v[110:113]
	v_mfma_f32_16x16x32_bf16 v[98:101], v[158:161], v[182:185], v[98:101]
	v_mfma_f32_16x16x32_bf16 v[94:97], v[166:169], v[182:185], v[94:97]
	v_mfma_f32_16x16x32_bf16 v[82:85], v[158:161], v[190:193], v[82:85]
	v_mfma_f32_16x16x32_bf16 v[78:81], v[166:169], v[190:193], v[78:81]
	v_mfma_f32_16x16x32_bf16 v[70:73], v[158:161], v[198:201], v[70:73]
	v_mfma_f32_16x16x32_bf16 v[66:69], v[166:169], v[198:201], v[66:69]
	s_barrier
	ds_read_b128 v[170:173], v137 offset:16384
	ds_read_b128 v[174:177], v137 offset:17408
	ds_read_b128 v[178:181], v137 offset:18432
	ds_read_b128 v[182:185], v137 offset:19456
	ds_read_b128 v[186:189], v137 offset:20480
	ds_read_b128 v[190:193], v137 offset:21504
	ds_read_b128 v[194:197], v137 offset:22528
	ds_read_b128 v[198:201], v137 offset:23552
	s_mov_b32 m0, s29
	s_nop 0
	buffer_load_dwordx4 v134, s[12:15], s56 offen lds
	s_add_i32 s57, s56, 0xb0000
	s_mov_b32 m0, s33
	s_nop 0
	buffer_load_dwordx4 v135, s[12:15], s56 offen lds
	s_nop 0
	s_mov_b32 m0, s34
	s_nop 0
	buffer_load_dwordx4 v134, s[12:15], s57 offen lds
	s_nop 0
	s_mov_b32 m0, s35
	s_nop 0
	buffer_load_dwordx4 v135, s[12:15], s57 offen lds
	s_nop 0
	s_mov_b32 m0, s28
	s_nop 0
	buffer_load_dwordx4 v134, s[16:19], s58 offen lds
	s_nop 0
	s_mov_b32 m0, s37
	s_nop 0
	buffer_load_dwordx4 v135, s[16:19], s58 offen lds
	s_waitcnt vmcnt(8)
	s_waitcnt lgkmcnt(0)
	s_barrier
	s_waitcnt lgkmcnt(7)
	v_mfma_f32_16x16x32_bf16 v[62:65], v[138:141], v[170:173], v[62:65]
	v_mfma_f32_16x16x32_bf16 v[58:61], v[146:149], v[170:173], v[58:61]
	s_waitcnt lgkmcnt(5)
	v_mfma_f32_16x16x32_bf16 v[54:57], v[138:141], v[178:181], v[54:57]
	v_mfma_f32_16x16x32_bf16 v[42:45], v[146:149], v[178:181], v[42:45]
	s_waitcnt lgkmcnt(3)
	v_mfma_f32_16x16x32_bf16 v[38:41], v[138:141], v[186:189], v[38:41]
	v_mfma_f32_16x16x32_bf16 v[26:29], v[146:149], v[186:189], v[26:29]
	s_waitcnt lgkmcnt(1)
	v_mfma_f32_16x16x32_bf16 v[18:21], v[138:141], v[194:197], v[18:21]
	v_mfma_f32_16x16x32_bf16 v[10:13], v[146:149], v[194:197], v[10:13]
	v_mfma_f32_16x16x32_bf16 v[62:65], v[142:145], v[174:177], v[62:65]
	v_mfma_f32_16x16x32_bf16 v[58:61], v[150:153], v[174:177], v[58:61]
	v_mfma_f32_16x16x32_bf16 v[54:57], v[142:145], v[182:185], v[54:57]
	v_mfma_f32_16x16x32_bf16 v[42:45], v[150:153], v[182:185], v[42:45]
	v_mfma_f32_16x16x32_bf16 v[38:41], v[142:145], v[190:193], v[38:41]
	v_mfma_f32_16x16x32_bf16 v[26:29], v[150:153], v[190:193], v[26:29]
	s_waitcnt lgkmcnt(0)
	v_mfma_f32_16x16x32_bf16 v[18:21], v[142:145], v[198:201], v[18:21]
	v_mfma_f32_16x16x32_bf16 v[10:13], v[150:153], v[198:201], v[10:13]
	v_mfma_f32_16x16x32_bf16 v[50:53], v[154:157], v[170:173], v[50:53]
	v_mfma_f32_16x16x32_bf16 v[46:49], v[162:165], v[170:173], v[46:49]
	v_mfma_f32_16x16x32_bf16 v[34:37], v[154:157], v[178:181], v[34:37]
	v_mfma_f32_16x16x32_bf16 v[30:33], v[162:165], v[178:181], v[30:33]
	v_mfma_f32_16x16x32_bf16 v[22:25], v[154:157], v[186:189], v[22:25]
	v_mfma_f32_16x16x32_bf16 v[14:17], v[162:165], v[186:189], v[14:17]
	v_mfma_f32_16x16x32_bf16 v[6:9], v[154:157], v[194:197], v[6:9]
	v_mfma_f32_16x16x32_bf16 v[2:5], v[162:165], v[194:197], v[2:5]
	v_mfma_f32_16x16x32_bf16 v[50:53], v[158:161], v[174:177], v[50:53]
	v_mfma_f32_16x16x32_bf16 v[46:49], v[166:169], v[174:177], v[46:49]
	v_mfma_f32_16x16x32_bf16 v[34:37], v[158:161], v[182:185], v[34:37]
	v_mfma_f32_16x16x32_bf16 v[30:33], v[166:169], v[182:185], v[30:33]
	v_mfma_f32_16x16x32_bf16 v[22:25], v[158:161], v[190:193], v[22:25]
	v_mfma_f32_16x16x32_bf16 v[14:17], v[166:169], v[190:193], v[14:17]
	v_mfma_f32_16x16x32_bf16 v[6:9], v[158:161], v[198:201], v[6:9]
	v_mfma_f32_16x16x32_bf16 v[2:5], v[166:169], v[198:201], v[2:5]
	s_barrier
	v_add_u32_e32 v150, 0x18000, v136
	v_add_u32_e32 v166, 0x1c000, v136
	ds_read_b128 v[138:141], v150
	ds_read_b128 v[142:145], v150 offset:1024
	ds_read_b128 v[146:149], v150 offset:2048
	ds_read_b128 v[150:153], v150 offset:3072
	ds_read_b128 v[154:157], v166
	ds_read_b128 v[158:161], v166 offset:1024
	ds_read_b128 v[162:165], v166 offset:2048
	ds_read_b128 v[166:169], v166 offset:3072
	ds_read_b128 v[170:173], v137 offset:32768
	ds_read_b128 v[174:177], v137 offset:33792
	ds_read_b128 v[178:181], v137 offset:34816
	ds_read_b128 v[182:185], v137 offset:35840
	ds_read_b128 v[186:189], v137 offset:36864
	ds_read_b128 v[190:193], v137 offset:37888
	ds_read_b128 v[194:197], v137 offset:38912
	ds_read_b128 v[198:201], v137 offset:39936
	s_add_i32 s57, s58, 0xb0000
	s_mov_b32 m0, s38
	s_nop 0
	buffer_load_dwordx4 v134, s[16:19], s57 offen lds
	s_nop 0
	s_mov_b32 m0, s39
	s_nop 0
	buffer_load_dwordx4 v135, s[16:19], s57 offen lds
	s_waitcnt vmcnt(8)
	s_waitcnt lgkmcnt(0)
	s_barrier
	s_waitcnt lgkmcnt(7)
	v_mfma_f32_16x16x32_bf16 v[126:129], v[138:141], v[170:173], v[126:129]
	v_mfma_f32_16x16x32_bf16 v[122:125], v[146:149], v[170:173], v[122:125]
	s_waitcnt lgkmcnt(5)
	v_mfma_f32_16x16x32_bf16 v[118:121], v[138:141], v[178:181], v[118:121]
	v_mfma_f32_16x16x32_bf16 v[106:109], v[146:149], v[178:181], v[106:109]
	s_waitcnt lgkmcnt(3)
	v_mfma_f32_16x16x32_bf16 v[102:105], v[138:141], v[186:189], v[102:105]
	v_mfma_f32_16x16x32_bf16 v[90:93], v[146:149], v[186:189], v[90:93]
	s_waitcnt lgkmcnt(1)
	v_mfma_f32_16x16x32_bf16 v[86:89], v[138:141], v[194:197], v[86:89]
	v_mfma_f32_16x16x32_bf16 v[74:77], v[146:149], v[194:197], v[74:77]
	v_mfma_f32_16x16x32_bf16 v[126:129], v[142:145], v[174:177], v[126:129]
	v_mfma_f32_16x16x32_bf16 v[122:125], v[150:153], v[174:177], v[122:125]
	v_mfma_f32_16x16x32_bf16 v[118:121], v[142:145], v[182:185], v[118:121]
	v_mfma_f32_16x16x32_bf16 v[106:109], v[150:153], v[182:185], v[106:109]
	v_mfma_f32_16x16x32_bf16 v[102:105], v[142:145], v[190:193], v[102:105]
	v_mfma_f32_16x16x32_bf16 v[90:93], v[150:153], v[190:193], v[90:93]
	s_waitcnt lgkmcnt(0)
	v_mfma_f32_16x16x32_bf16 v[86:89], v[142:145], v[198:201], v[86:89]
	v_mfma_f32_16x16x32_bf16 v[74:77], v[150:153], v[198:201], v[74:77]
	v_mfma_f32_16x16x32_bf16 v[114:117], v[154:157], v[170:173], v[114:117]
	v_mfma_f32_16x16x32_bf16 v[110:113], v[162:165], v[170:173], v[110:113]
	v_mfma_f32_16x16x32_bf16 v[98:101], v[154:157], v[178:181], v[98:101]
	v_mfma_f32_16x16x32_bf16 v[94:97], v[162:165], v[178:181], v[94:97]
	v_mfma_f32_16x16x32_bf16 v[82:85], v[154:157], v[186:189], v[82:85]
	v_mfma_f32_16x16x32_bf16 v[78:81], v[162:165], v[186:189], v[78:81]
	v_mfma_f32_16x16x32_bf16 v[70:73], v[154:157], v[194:197], v[70:73]
	v_mfma_f32_16x16x32_bf16 v[66:69], v[162:165], v[194:197], v[66:69]
	v_mfma_f32_16x16x32_bf16 v[114:117], v[158:161], v[174:177], v[114:117]
	v_mfma_f32_16x16x32_bf16 v[110:113], v[166:169], v[174:177], v[110:113]
	v_mfma_f32_16x16x32_bf16 v[98:101], v[158:161], v[182:185], v[98:101]
	v_mfma_f32_16x16x32_bf16 v[94:97], v[166:169], v[182:185], v[94:97]
	v_mfma_f32_16x16x32_bf16 v[82:85], v[158:161], v[190:193], v[82:85]
	v_mfma_f32_16x16x32_bf16 v[78:81], v[166:169], v[190:193], v[78:81]
	v_mfma_f32_16x16x32_bf16 v[70:73], v[158:161], v[198:201], v[70:73]
	v_mfma_f32_16x16x32_bf16 v[66:69], v[166:169], v[198:201], v[66:69]
	s_barrier
	ds_read_b128 v[170:173], v137 offset:49152
	ds_read_b128 v[174:177], v137 offset:50176
	ds_read_b128 v[178:181], v137 offset:51200
	ds_read_b128 v[182:185], v137 offset:52224
	ds_read_b128 v[186:189], v137 offset:53248
	ds_read_b128 v[190:193], v137 offset:54272
	ds_read_b128 v[194:197], v137 offset:55296
	ds_read_b128 v[198:201], v137 offset:56320
	s_add_i32 s57, s56, 0x80
	s_mov_b32 m0, s40
	s_nop 0
	buffer_load_dwordx4 v134, s[12:15], s57 offen lds
	s_add_i32 s56, s56, 0xb0080
	s_mov_b32 m0, s41
	s_nop 0
	buffer_load_dwordx4 v135, s[12:15], s57 offen lds
	s_nop 0
	s_mov_b32 m0, s44
	s_nop 0
	buffer_load_dwordx4 v134, s[12:15], s56 offen lds
	s_nop 0
	s_mov_b32 m0, s45
	s_nop 0
	buffer_load_dwordx4 v135, s[12:15], s56 offen lds
	s_nop 0
	s_mov_b32 m0, s42
	s_nop 0
	buffer_load_dwordx4 v134, s[16:19], s55 offen lds
	s_nop 0
	s_mov_b32 m0, s43
	s_nop 0
	buffer_load_dwordx4 v135, s[16:19], s55 offen lds
	s_waitcnt vmcnt(8)
	s_waitcnt lgkmcnt(0)
	s_barrier
	s_waitcnt lgkmcnt(7)
	v_mfma_f32_16x16x32_bf16 v[62:65], v[138:141], v[170:173], v[62:65]
	v_mfma_f32_16x16x32_bf16 v[58:61], v[146:149], v[170:173], v[58:61]
	s_waitcnt lgkmcnt(5)
	v_mfma_f32_16x16x32_bf16 v[54:57], v[138:141], v[178:181], v[54:57]
	v_mfma_f32_16x16x32_bf16 v[42:45], v[146:149], v[178:181], v[42:45]
	s_waitcnt lgkmcnt(3)
	v_mfma_f32_16x16x32_bf16 v[38:41], v[138:141], v[186:189], v[38:41]
	v_mfma_f32_16x16x32_bf16 v[26:29], v[146:149], v[186:189], v[26:29]
	s_waitcnt lgkmcnt(1)
	v_mfma_f32_16x16x32_bf16 v[18:21], v[138:141], v[194:197], v[18:21]
	v_mfma_f32_16x16x32_bf16 v[10:13], v[146:149], v[194:197], v[10:13]
	v_mfma_f32_16x16x32_bf16 v[62:65], v[142:145], v[174:177], v[62:65]
	v_mfma_f32_16x16x32_bf16 v[58:61], v[150:153], v[174:177], v[58:61]
	v_mfma_f32_16x16x32_bf16 v[54:57], v[142:145], v[182:185], v[54:57]
	v_mfma_f32_16x16x32_bf16 v[42:45], v[150:153], v[182:185], v[42:45]
	v_mfma_f32_16x16x32_bf16 v[38:41], v[142:145], v[190:193], v[38:41]
	v_mfma_f32_16x16x32_bf16 v[26:29], v[150:153], v[190:193], v[26:29]
	s_waitcnt lgkmcnt(0)
	v_mfma_f32_16x16x32_bf16 v[18:21], v[142:145], v[198:201], v[18:21]
	v_mfma_f32_16x16x32_bf16 v[10:13], v[150:153], v[198:201], v[10:13]
	v_mfma_f32_16x16x32_bf16 v[50:53], v[154:157], v[170:173], v[50:53]
	v_mfma_f32_16x16x32_bf16 v[46:49], v[162:165], v[170:173], v[46:49]
	v_mfma_f32_16x16x32_bf16 v[34:37], v[154:157], v[178:181], v[34:37]
	v_mfma_f32_16x16x32_bf16 v[30:33], v[162:165], v[178:181], v[30:33]
	v_mfma_f32_16x16x32_bf16 v[22:25], v[154:157], v[186:189], v[22:25]
	v_mfma_f32_16x16x32_bf16 v[14:17], v[162:165], v[186:189], v[14:17]
	v_mfma_f32_16x16x32_bf16 v[6:9], v[154:157], v[194:197], v[6:9]
	v_mfma_f32_16x16x32_bf16 v[2:5], v[162:165], v[194:197], v[2:5]
	v_mfma_f32_16x16x32_bf16 v[50:53], v[158:161], v[174:177], v[50:53]
	v_mfma_f32_16x16x32_bf16 v[46:49], v[166:169], v[174:177], v[46:49]
	v_mfma_f32_16x16x32_bf16 v[34:37], v[158:161], v[182:185], v[34:37]
	v_mfma_f32_16x16x32_bf16 v[30:33], v[166:169], v[182:185], v[30:33]
	v_mfma_f32_16x16x32_bf16 v[22:25], v[158:161], v[190:193], v[22:25]
	v_mfma_f32_16x16x32_bf16 v[14:17], v[166:169], v[190:193], v[14:17]
	v_mfma_f32_16x16x32_bf16 v[6:9], v[158:161], v[198:201], v[6:9]
	v_mfma_f32_16x16x32_bf16 v[2:5], v[166:169], v[198:201], v[2:5]
	s_barrier
	s_add_i32 s2, s2, 2
	s_addk_i32 s3, 0x100
	s_cmp_gt_u32 s2, 41
	s_cbranch_scc0 .LBB0_1135
	s_andn2_b64 vcc, exec, s[4:5]
	s_cbranch_vccnz .LBB0_1123
	v_mov_b32_e32 v2, 0
	s_mov_b32 s20, s50
	s_mov_b32 s25, s51
	s_mov_b32 s30, s54
	s_mov_b32 s36, s53
	s_mov_b32 s49, s52
	v_mov_b32_e32 v3, v2
	v_mov_b32_e32 v4, v2
	v_mov_b32_e32 v5, v2
	v_mov_b32_e32 v6, v2
	v_mov_b32_e32 v7, v2
	v_mov_b32_e32 v8, v2
	v_mov_b32_e32 v9, v2
	v_mov_b32_e32 v14, v2
	v_mov_b32_e32 v15, v2
	v_mov_b32_e32 v16, v2
	v_mov_b32_e32 v17, v2
	v_mov_b32_e32 v22, v2
	v_mov_b32_e32 v23, v2
	v_mov_b32_e32 v24, v2
	v_mov_b32_e32 v25, v2
	v_mov_b32_e32 v30, v2
	v_mov_b32_e32 v31, v2
	v_mov_b32_e32 v32, v2
	v_mov_b32_e32 v33, v2
	v_mov_b32_e32 v34, v2
	v_mov_b32_e32 v35, v2
	v_mov_b32_e32 v36, v2
	v_mov_b32_e32 v37, v2
	v_mov_b32_e32 v46, v2
	v_mov_b32_e32 v47, v2
	v_mov_b32_e32 v48, v2
	v_mov_b32_e32 v49, v2
	v_mov_b32_e32 v50, v2
	v_mov_b32_e32 v51, v2
	v_mov_b32_e32 v52, v2
	v_mov_b32_e32 v53, v2
	v_mov_b32_e32 v10, v2
	v_mov_b32_e32 v11, v2
	v_mov_b32_e32 v12, v2
	v_mov_b32_e32 v13, v2
	v_mov_b32_e32 v18, v2
	v_mov_b32_e32 v19, v2
	v_mov_b32_e32 v20, v2
	v_mov_b32_e32 v21, v2
	v_mov_b32_e32 v26, v2
	v_mov_b32_e32 v27, v2
	v_mov_b32_e32 v28, v2
	v_mov_b32_e32 v29, v2
	v_mov_b32_e32 v38, v2
	v_mov_b32_e32 v39, v2
	v_mov_b32_e32 v40, v2
	v_mov_b32_e32 v41, v2
	v_mov_b32_e32 v42, v2
	v_mov_b32_e32 v43, v2
	v_mov_b32_e32 v44, v2
	v_mov_b32_e32 v45, v2
	v_mov_b32_e32 v54, v2
	v_mov_b32_e32 v55, v2
	v_mov_b32_e32 v56, v2
	v_mov_b32_e32 v57, v2
	v_mov_b32_e32 v58, v2
	v_mov_b32_e32 v59, v2
	v_mov_b32_e32 v60, v2
	v_mov_b32_e32 v61, v2
	v_mov_b32_e32 v62, v2
	v_mov_b32_e32 v63, v2
	v_mov_b32_e32 v64, v2
	v_mov_b32_e32 v65, v2
	v_mov_b32_e32 v66, v2
	v_mov_b32_e32 v67, v2
	v_mov_b32_e32 v68, v2
	v_mov_b32_e32 v69, v2
	v_mov_b32_e32 v70, v2
	v_mov_b32_e32 v71, v2
	v_mov_b32_e32 v72, v2
	v_mov_b32_e32 v73, v2
	v_mov_b32_e32 v78, v2
	v_mov_b32_e32 v79, v2
	v_mov_b32_e32 v80, v2
	v_mov_b32_e32 v81, v2
	v_mov_b32_e32 v82, v2
	v_mov_b32_e32 v83, v2
	v_mov_b32_e32 v84, v2
	v_mov_b32_e32 v85, v2
	v_mov_b32_e32 v94, v2
	v_mov_b32_e32 v95, v2
	v_mov_b32_e32 v96, v2
	v_mov_b32_e32 v97, v2
	v_mov_b32_e32 v98, v2
	v_mov_b32_e32 v99, v2
	v_mov_b32_e32 v100, v2
	v_mov_b32_e32 v101, v2
	v_mov_b32_e32 v110, v2
	v_mov_b32_e32 v111, v2
	v_mov_b32_e32 v112, v2
	v_mov_b32_e32 v113, v2
	v_mov_b32_e32 v114, v2
	v_mov_b32_e32 v115, v2
	v_mov_b32_e32 v116, v2
	v_mov_b32_e32 v117, v2
	v_mov_b32_e32 v74, v2
	v_mov_b32_e32 v75, v2
	v_mov_b32_e32 v76, v2
	v_mov_b32_e32 v77, v2
	v_mov_b32_e32 v86, v2
	v_mov_b32_e32 v87, v2
	v_mov_b32_e32 v88, v2
	v_mov_b32_e32 v89, v2
	v_mov_b32_e32 v90, v2
	v_mov_b32_e32 v91, v2
	v_mov_b32_e32 v92, v2
	v_mov_b32_e32 v93, v2
	v_mov_b32_e32 v102, v2
	v_mov_b32_e32 v103, v2
	v_mov_b32_e32 v104, v2
	v_mov_b32_e32 v105, v2
	v_mov_b32_e32 v106, v2
	v_mov_b32_e32 v107, v2
	v_mov_b32_e32 v108, v2
	v_mov_b32_e32 v109, v2
	v_mov_b32_e32 v118, v2
	v_mov_b32_e32 v119, v2
	v_mov_b32_e32 v120, v2
	v_mov_b32_e32 v121, v2
	v_mov_b32_e32 v122, v2
	v_mov_b32_e32 v123, v2
	v_mov_b32_e32 v124, v2
	v_mov_b32_e32 v125, v2
	v_mov_b32_e32 v126, v2
	v_mov_b32_e32 v127, v2
	v_mov_b32_e32 v128, v2
	v_mov_b32_e32 v129, v2
	s_branch .LBB0_1123
